# attention (phase 7) output: 8-byte stores widened to 16-byte with v_permlane16_swap
# speedup vs baseline: 1.0188x; 1.0004x over previous
.LBB0_501:
	s_lshl_b32 s0, s9, 2
	s_and_b32 s6, s0, 0xffffff00
	s_lshl_b32 s0, s9, 8
	s_and_b32 s7, s0, 0x300
	v_or_b32_e32 v252, s6, v187
	v_lshlrev_b32_e32 v252, 11, v252
	s_lshl_b32 s0, s7, 1
	v_add3_u32 v252, v252, v190, s0
	s_mov_b64 s[14:15], s[64:65]
	v_add_u32_e32 v253, 0x10800, v196
	global_load_dwordx4 v[4:7], v252, s[14:15]
	s_add_u32 s14, s14, 0x8000
	s_addc_u32 s15, s15, 0
	global_load_dwordx4 v[8:11], v252, s[14:15]
	s_add_u32 s14, s14, 0x8000
	s_addc_u32 s15, s15, 0
	global_load_dwordx4 v[12:15], v252, s[14:15]
	s_add_u32 s14, s14, 0x8000
	s_addc_u32 s15, s15, 0
	global_load_dwordx4 v[16:19], v252, s[14:15]
	s_add_u32 s14, s14, 0x8000
	s_addc_u32 s15, s15, 0
	global_load_dwordx4 v[20:23], v252, s[14:15]
	s_add_u32 s14, s14, 0x8000
	s_addc_u32 s15, s15, 0
	global_load_dwordx4 v[24:27], v252, s[14:15]
	s_add_u32 s14, s14, 0x8000
	s_addc_u32 s15, s15, 0
	global_load_dwordx4 v[28:31], v252, s[14:15]
	s_add_u32 s14, s14, 0x8000
	s_addc_u32 s15, s15, 0
	global_load_dwordx4 v[32:35], v252, s[14:15]
	s_add_u32 s14, s14, 0x8000
	s_addc_u32 s15, s15, 0
	global_load_dwordx4 v[36:39], v252, s[14:15]
	s_add_u32 s14, s14, 0x8000
	s_addc_u32 s15, s15, 0
	global_load_dwordx4 v[40:43], v252, s[14:15]
	s_add_u32 s14, s14, 0x8000
	s_addc_u32 s15, s15, 0
	global_load_dwordx4 v[44:47], v252, s[14:15]
	s_add_u32 s14, s14, 0x8000
	s_addc_u32 s15, s15, 0
	global_load_dwordx4 v[48:51], v252, s[14:15]
	s_add_u32 s14, s14, 0x8000
	s_addc_u32 s15, s15, 0
	global_load_dwordx4 v[52:55], v252, s[14:15]
	s_add_u32 s14, s14, 0x8000
	s_addc_u32 s15, s15, 0
	global_load_dwordx4 v[56:59], v252, s[14:15]
	s_add_u32 s14, s14, 0x8000
	s_addc_u32 s15, s15, 0
	global_load_dwordx4 v[128:131], v252, s[14:15]
	s_add_u32 s14, s14, 0x8000
	s_addc_u32 s15, s15, 0
	global_load_dwordx4 v[132:135], v252, s[14:15]
	s_add_u32 s14, s14, 0x8000
	s_addc_u32 s15, s15, 0
	s_lshl_b32 s0, s9, 6
	s_and_b32 s0, s0, 0xffffff00
	v_add_u32_e32 v0, s0, v197
	v_ashrrev_i32_e32 v1, 31, v0
	v_lshlrev_b64 v[194:195], 10, v[0:1]
	v_lshlrev_b64 v[0:1], 11, v[0:1]
	v_lshl_add_u64 v[0:1], s[58:59], 0, v[0:1]
	s_lshl_b32 s0, s7, 1
	v_lshl_add_u64 v[0:1], v[0:1], 0, s[0:1]
	v_lshl_add_u64 v[0:1], v[0:1], 0, v[192:193]
	global_load_dwordx4 v[112:115], v[0:1], off
	v_add_co_u32_e32 v2, vcc, 0x8000, v0
	v_readlane_b32 s12, v254, 37
	s_nop 0
	v_addc_co_u32_e32 v3, vcc, 0, v1, vcc
	global_load_dwordx4 v[124:127], v[2:3], off
	global_load_dwordx4 v[116:119], v[0:1], off offset:64
	global_load_dwordx4 v[120:123], v[2:3], off offset:64
	global_load_dwordx4 v[104:107], v[0:1], off offset:128
	global_load_dwordx4 v[108:111], v[2:3], off offset:128
	global_load_dwordx4 v[96:99], v[0:1], off offset:192
	global_load_dwordx4 v[100:103], v[2:3], off offset:192
	global_load_dwordx4 v[88:91], v[0:1], off offset:256
	global_load_dwordx4 v[92:95], v[2:3], off offset:256
	global_load_dwordx4 v[80:83], v[0:1], off offset:320
	global_load_dwordx4 v[84:87], v[2:3], off offset:320
	global_load_dwordx4 v[68:71], v[0:1], off offset:384
	global_load_dwordx4 v[72:75], v[2:3], off offset:384
	global_load_dwordx4 v[60:63], v[0:1], off offset:448
	global_load_dwordx4 v[76:79], v[2:3], off offset:448
	s_waitcnt vmcnt(31)
	ds_write_b128 v196, v[4:7]
	s_waitcnt vmcnt(30)
	ds_write_b128 v196, v[8:11] offset:8448
	s_waitcnt vmcnt(29)
	ds_write_b128 v196, v[12:15] offset:16896
	s_waitcnt vmcnt(28)
	ds_write_b128 v196, v[16:19] offset:25344
	s_waitcnt vmcnt(27)
	ds_write_b128 v196, v[20:23] offset:33792
	s_waitcnt vmcnt(26)
	ds_write_b128 v196, v[24:27] offset:42240
	s_waitcnt vmcnt(25)
	ds_write_b128 v196, v[28:31] offset:50688
	s_waitcnt vmcnt(24)
	ds_write_b128 v196, v[32:35] offset:59136
	s_waitcnt vmcnt(23)
	ds_write_b128 v253, v[36:39]
	s_waitcnt vmcnt(22)
	ds_write_b128 v253, v[40:43] offset:8448
	s_waitcnt vmcnt(21)
	ds_write_b128 v253, v[44:47] offset:16896
	s_waitcnt vmcnt(20)
	ds_write_b128 v253, v[48:51] offset:25344
	s_waitcnt vmcnt(19)
	ds_write_b128 v253, v[52:55] offset:33792
	s_waitcnt vmcnt(18)
	ds_write_b128 v253, v[56:59] offset:42240
	s_waitcnt vmcnt(17)
	ds_write_b128 v253, v[128:131] offset:50688
	s_waitcnt vmcnt(16)
	ds_write_b128 v253, v[132:135] offset:59136
	s_waitcnt lgkmcnt(0)
	s_barrier
	v_readlane_b32 s13, v254, 38
	s_mov_b32 s10, 0
	ds_read_b128 v[228:231], v212
	ds_read_b128 v[232:235], v212 offset:64
	ds_read_b128 v[236:239], v212 offset:128
	ds_read_b128 v[240:243], v212 offset:192
	ds_read_b128 v[244:247], v212 offset:256
	s_waitcnt vmcnt(0)
	s_waitcnt lgkmcnt(4)
	v_mfma_f32_16x16x32_bf16 v[64:67], v[228:231], v[112:115], 0
	v_mfma_f32_16x16x32_bf16 v[0:3], v[228:231], v[124:127], 0
	ds_read_b128 v[228:231], v212 offset:320
	s_waitcnt lgkmcnt(4)
	v_mfma_f32_16x16x32_bf16 v[64:67], v[232:235], v[116:119], v[64:67]
	v_mfma_f32_16x16x32_bf16 v[0:3], v[232:235], v[120:123], v[0:3]
	ds_read_b128 v[232:235], v212 offset:384
	s_waitcnt lgkmcnt(4)
	v_mfma_f32_16x16x32_bf16 v[64:67], v[236:239], v[104:107], v[64:67]
	v_mfma_f32_16x16x32_bf16 v[0:3], v[236:239], v[108:111], v[0:3]
	ds_read_b128 v[236:239], v212 offset:448
	s_waitcnt lgkmcnt(4)
	v_mfma_f32_16x16x32_bf16 v[64:67], v[240:243], v[96:99], v[64:67]
	v_mfma_f32_16x16x32_bf16 v[0:3], v[240:243], v[100:103], v[0:3]
	ds_read_b128 v[240:243], v212 offset:8448
	s_waitcnt lgkmcnt(4)
	v_mfma_f32_16x16x32_bf16 v[64:67], v[244:247], v[88:91], v[64:67]
	v_mfma_f32_16x16x32_bf16 v[0:3], v[244:247], v[92:95], v[0:3]
	ds_read_b128 v[244:247], v212 offset:8512
	s_waitcnt lgkmcnt(4)
	v_mfma_f32_16x16x32_bf16 v[64:67], v[228:231], v[80:83], v[64:67]
	v_mfma_f32_16x16x32_bf16 v[0:3], v[228:231], v[84:87], v[0:3]
	ds_read_b128 v[228:231], v212 offset:8576
	s_waitcnt lgkmcnt(4)
	v_mfma_f32_16x16x32_bf16 v[64:67], v[232:235], v[68:71], v[64:67]
	v_mfma_f32_16x16x32_bf16 v[0:3], v[232:235], v[72:75], v[0:3]
	ds_read_b128 v[232:235], v212 offset:8640
	s_waitcnt lgkmcnt(4)
	v_mfma_f32_16x16x32_bf16 v[64:67], v[236:239], v[60:63], v[64:67]
	v_mfma_f32_16x16x32_bf16 v[0:3], v[236:239], v[76:79], v[0:3]
	ds_read_b128 v[236:239], v212 offset:8704
	s_waitcnt lgkmcnt(4)
	v_mfma_f32_16x16x32_bf16 v[128:131], v[240:243], v[112:115], 0
	v_mfma_f32_16x16x32_bf16 v[4:7], v[240:243], v[124:127], 0
	ds_read_b128 v[240:243], v212 offset:8768
	s_waitcnt lgkmcnt(4)
	v_mfma_f32_16x16x32_bf16 v[128:131], v[244:247], v[116:119], v[128:131]
	v_mfma_f32_16x16x32_bf16 v[4:7], v[244:247], v[120:123], v[4:7]
	ds_read_b128 v[244:247], v212 offset:8832
	s_waitcnt lgkmcnt(4)
	v_mfma_f32_16x16x32_bf16 v[128:131], v[228:231], v[104:107], v[128:131]
	v_mfma_f32_16x16x32_bf16 v[4:7], v[228:231], v[108:111], v[4:7]
	ds_read_b128 v[228:231], v212 offset:8896
	s_waitcnt lgkmcnt(4)
	v_mfma_f32_16x16x32_bf16 v[128:131], v[232:235], v[96:99], v[128:131]
	v_mfma_f32_16x16x32_bf16 v[4:7], v[232:235], v[100:103], v[4:7]
	ds_read_b128 v[232:235], v212 offset:16896
	s_waitcnt lgkmcnt(4)
	v_mfma_f32_16x16x32_bf16 v[128:131], v[236:239], v[88:91], v[128:131]
	v_mfma_f32_16x16x32_bf16 v[4:7], v[236:239], v[92:95], v[4:7]
	ds_read_b128 v[236:239], v212 offset:16960
	s_waitcnt lgkmcnt(4)
	v_mfma_f32_16x16x32_bf16 v[128:131], v[240:243], v[80:83], v[128:131]
	v_mfma_f32_16x16x32_bf16 v[4:7], v[240:243], v[84:87], v[4:7]
	ds_read_b128 v[240:243], v212 offset:17024
	s_waitcnt lgkmcnt(4)
	v_mfma_f32_16x16x32_bf16 v[128:131], v[244:247], v[68:71], v[128:131]
	v_mfma_f32_16x16x32_bf16 v[4:7], v[244:247], v[72:75], v[4:7]
	ds_read_b128 v[244:247], v212 offset:17088
	s_waitcnt lgkmcnt(4)
	v_mfma_f32_16x16x32_bf16 v[128:131], v[228:231], v[60:63], v[128:131]
	v_mfma_f32_16x16x32_bf16 v[4:7], v[228:231], v[76:79], v[4:7]
	ds_read_b128 v[228:231], v212 offset:17152
	s_waitcnt lgkmcnt(4)
	v_mfma_f32_16x16x32_bf16 v[132:135], v[232:235], v[112:115], 0
	v_mfma_f32_16x16x32_bf16 v[8:11], v[232:235], v[124:127], 0
	ds_read_b128 v[232:235], v212 offset:17216
	s_waitcnt lgkmcnt(4)
	v_mfma_f32_16x16x32_bf16 v[132:135], v[236:239], v[116:119], v[132:135]
	v_mfma_f32_16x16x32_bf16 v[8:11], v[236:239], v[120:123], v[8:11]
	ds_read_b128 v[236:239], v212 offset:17280
	s_waitcnt lgkmcnt(4)
	v_mfma_f32_16x16x32_bf16 v[132:135], v[240:243], v[104:107], v[132:135]
	v_mfma_f32_16x16x32_bf16 v[8:11], v[240:243], v[108:111], v[8:11]
	ds_read_b128 v[240:243], v212 offset:17344
	s_waitcnt lgkmcnt(4)
	v_mfma_f32_16x16x32_bf16 v[132:135], v[244:247], v[96:99], v[132:135]
	v_mfma_f32_16x16x32_bf16 v[8:11], v[244:247], v[100:103], v[8:11]
	ds_read_b128 v[244:247], v212 offset:25344
	s_waitcnt lgkmcnt(4)
	v_mfma_f32_16x16x32_bf16 v[132:135], v[228:231], v[88:91], v[132:135]
	v_mfma_f32_16x16x32_bf16 v[8:11], v[228:231], v[92:95], v[8:11]
	ds_read_b128 v[228:231], v212 offset:25408
	s_waitcnt lgkmcnt(4)
	v_mfma_f32_16x16x32_bf16 v[132:135], v[232:235], v[80:83], v[132:135]
	v_mfma_f32_16x16x32_bf16 v[8:11], v[232:235], v[84:87], v[8:11]
	ds_read_b128 v[232:235], v212 offset:25472
	s_waitcnt lgkmcnt(4)
	v_mfma_f32_16x16x32_bf16 v[132:135], v[236:239], v[68:71], v[132:135]
	v_mfma_f32_16x16x32_bf16 v[8:11], v[236:239], v[72:75], v[8:11]
	ds_read_b128 v[236:239], v212 offset:25536
	s_waitcnt lgkmcnt(4)
	v_mfma_f32_16x16x32_bf16 v[132:135], v[240:243], v[60:63], v[132:135]
	v_mfma_f32_16x16x32_bf16 v[8:11], v[240:243], v[76:79], v[8:11]
	ds_read_b128 v[240:243], v212 offset:25600
	s_waitcnt lgkmcnt(4)
	v_mfma_f32_16x16x32_bf16 v[136:139], v[244:247], v[112:115], 0
	v_mfma_f32_16x16x32_bf16 v[12:15], v[244:247], v[124:127], 0
	ds_read_b128 v[244:247], v212 offset:25664
	s_waitcnt lgkmcnt(4)
	v_mfma_f32_16x16x32_bf16 v[136:139], v[228:231], v[116:119], v[136:139]
	v_mfma_f32_16x16x32_bf16 v[12:15], v[228:231], v[120:123], v[12:15]
	ds_read_b128 v[228:231], v212 offset:25728
	s_waitcnt lgkmcnt(4)
	v_mfma_f32_16x16x32_bf16 v[136:139], v[232:235], v[104:107], v[136:139]
	v_mfma_f32_16x16x32_bf16 v[12:15], v[232:235], v[108:111], v[12:15]
	ds_read_b128 v[232:235], v212 offset:25792
	s_waitcnt lgkmcnt(4)
	v_mfma_f32_16x16x32_bf16 v[136:139], v[236:239], v[96:99], v[136:139]
	v_mfma_f32_16x16x32_bf16 v[12:15], v[236:239], v[100:103], v[12:15]
	ds_read_b128 v[236:239], v212 offset:33792
	s_waitcnt lgkmcnt(4)
	v_mfma_f32_16x16x32_bf16 v[136:139], v[240:243], v[88:91], v[136:139]
	v_mfma_f32_16x16x32_bf16 v[12:15], v[240:243], v[92:95], v[12:15]
	ds_read_b128 v[240:243], v212 offset:33856
	s_waitcnt lgkmcnt(4)
	v_mfma_f32_16x16x32_bf16 v[136:139], v[244:247], v[80:83], v[136:139]
	v_mfma_f32_16x16x32_bf16 v[12:15], v[244:247], v[84:87], v[12:15]
	ds_read_b128 v[244:247], v212 offset:33920
	s_waitcnt lgkmcnt(4)
	v_mfma_f32_16x16x32_bf16 v[136:139], v[228:231], v[68:71], v[136:139]
	v_mfma_f32_16x16x32_bf16 v[12:15], v[228:231], v[72:75], v[12:15]
	ds_read_b128 v[228:231], v212 offset:33984
	s_waitcnt lgkmcnt(4)
	v_mfma_f32_16x16x32_bf16 v[136:139], v[232:235], v[60:63], v[136:139]
	v_mfma_f32_16x16x32_bf16 v[12:15], v[232:235], v[76:79], v[12:15]
	ds_read_b128 v[232:235], v212 offset:34048
	s_waitcnt lgkmcnt(4)
	v_mfma_f32_16x16x32_bf16 v[140:143], v[236:239], v[112:115], 0
	v_mfma_f32_16x16x32_bf16 v[16:19], v[236:239], v[124:127], 0
	ds_read_b128 v[236:239], v212 offset:34112
	s_waitcnt lgkmcnt(4)
	v_mfma_f32_16x16x32_bf16 v[140:143], v[240:243], v[116:119], v[140:143]
	v_mfma_f32_16x16x32_bf16 v[16:19], v[240:243], v[120:123], v[16:19]
	ds_read_b128 v[240:243], v212 offset:34176
	s_waitcnt lgkmcnt(4)
	v_mfma_f32_16x16x32_bf16 v[140:143], v[244:247], v[104:107], v[140:143]
	v_mfma_f32_16x16x32_bf16 v[16:19], v[244:247], v[108:111], v[16:19]
	ds_read_b128 v[244:247], v212 offset:34240
	s_waitcnt lgkmcnt(4)
	v_mfma_f32_16x16x32_bf16 v[140:143], v[228:231], v[96:99], v[140:143]
	v_mfma_f32_16x16x32_bf16 v[16:19], v[228:231], v[100:103], v[16:19]
	ds_read_b128 v[228:231], v212 offset:42240
	s_waitcnt lgkmcnt(4)
	v_mfma_f32_16x16x32_bf16 v[140:143], v[232:235], v[88:91], v[140:143]
	v_mfma_f32_16x16x32_bf16 v[16:19], v[232:235], v[92:95], v[16:19]
	ds_read_b128 v[232:235], v212 offset:42304
	s_waitcnt lgkmcnt(4)
	v_mfma_f32_16x16x32_bf16 v[140:143], v[236:239], v[80:83], v[140:143]
	v_mfma_f32_16x16x32_bf16 v[16:19], v[236:239], v[84:87], v[16:19]
	ds_read_b128 v[236:239], v212 offset:42368
	s_waitcnt lgkmcnt(4)
	v_mfma_f32_16x16x32_bf16 v[140:143], v[240:243], v[68:71], v[140:143]
	v_mfma_f32_16x16x32_bf16 v[16:19], v[240:243], v[72:75], v[16:19]
	ds_read_b128 v[240:243], v212 offset:42432
	s_waitcnt lgkmcnt(4)
	v_mfma_f32_16x16x32_bf16 v[140:143], v[244:247], v[60:63], v[140:143]
	v_mfma_f32_16x16x32_bf16 v[16:19], v[244:247], v[76:79], v[16:19]
	ds_read_b128 v[244:247], v212 offset:42496
	s_waitcnt lgkmcnt(4)
	v_mfma_f32_16x16x32_bf16 v[144:147], v[228:231], v[112:115], 0
	v_mfma_f32_16x16x32_bf16 v[20:23], v[228:231], v[124:127], 0
	ds_read_b128 v[228:231], v212 offset:42560
	s_waitcnt lgkmcnt(4)
	v_mfma_f32_16x16x32_bf16 v[144:147], v[232:235], v[116:119], v[144:147]
	v_mfma_f32_16x16x32_bf16 v[20:23], v[232:235], v[120:123], v[20:23]
	ds_read_b128 v[232:235], v212 offset:42624
	s_waitcnt lgkmcnt(4)
	v_mfma_f32_16x16x32_bf16 v[144:147], v[236:239], v[104:107], v[144:147]
	v_mfma_f32_16x16x32_bf16 v[20:23], v[236:239], v[108:111], v[20:23]
	ds_read_b128 v[236:239], v212 offset:42688
	s_waitcnt lgkmcnt(4)
	v_mfma_f32_16x16x32_bf16 v[144:147], v[240:243], v[96:99], v[144:147]
	v_mfma_f32_16x16x32_bf16 v[20:23], v[240:243], v[100:103], v[20:23]
	ds_read_b128 v[240:243], v212 offset:50688
	s_waitcnt lgkmcnt(4)
	v_mfma_f32_16x16x32_bf16 v[144:147], v[244:247], v[88:91], v[144:147]
	v_mfma_f32_16x16x32_bf16 v[20:23], v[244:247], v[92:95], v[20:23]
	ds_read_b128 v[244:247], v212 offset:50752
	s_waitcnt lgkmcnt(4)
	v_mfma_f32_16x16x32_bf16 v[144:147], v[228:231], v[80:83], v[144:147]
	v_mfma_f32_16x16x32_bf16 v[20:23], v[228:231], v[84:87], v[20:23]
	ds_read_b128 v[228:231], v212 offset:50816
	s_waitcnt lgkmcnt(4)
	v_mfma_f32_16x16x32_bf16 v[144:147], v[232:235], v[68:71], v[144:147]
	v_mfma_f32_16x16x32_bf16 v[20:23], v[232:235], v[72:75], v[20:23]
	ds_read_b128 v[232:235], v212 offset:50880
	s_waitcnt lgkmcnt(4)
	v_mfma_f32_16x16x32_bf16 v[144:147], v[236:239], v[60:63], v[144:147]
	v_mfma_f32_16x16x32_bf16 v[20:23], v[236:239], v[76:79], v[20:23]
	ds_read_b128 v[236:239], v212 offset:50944
	s_waitcnt lgkmcnt(4)
	v_mfma_f32_16x16x32_bf16 v[148:151], v[240:243], v[112:115], 0
	v_mfma_f32_16x16x32_bf16 v[24:27], v[240:243], v[124:127], 0
	ds_read_b128 v[240:243], v212 offset:51008
	s_waitcnt lgkmcnt(4)
	v_mfma_f32_16x16x32_bf16 v[148:151], v[244:247], v[116:119], v[148:151]
	v_mfma_f32_16x16x32_bf16 v[24:27], v[244:247], v[120:123], v[24:27]
	ds_read_b128 v[244:247], v212 offset:51072
	s_waitcnt lgkmcnt(4)
	v_mfma_f32_16x16x32_bf16 v[148:151], v[228:231], v[104:107], v[148:151]
	v_mfma_f32_16x16x32_bf16 v[24:27], v[228:231], v[108:111], v[24:27]
	ds_read_b128 v[228:231], v212 offset:51136
	s_waitcnt lgkmcnt(4)
	v_mfma_f32_16x16x32_bf16 v[148:151], v[232:235], v[96:99], v[148:151]
	v_mfma_f32_16x16x32_bf16 v[24:27], v[232:235], v[100:103], v[24:27]
	ds_read_b128 v[232:235], v212 offset:59136
	s_waitcnt lgkmcnt(4)
	v_mfma_f32_16x16x32_bf16 v[148:151], v[236:239], v[88:91], v[148:151]
	v_mfma_f32_16x16x32_bf16 v[24:27], v[236:239], v[92:95], v[24:27]
	ds_read_b128 v[236:239], v212 offset:59200
	s_waitcnt lgkmcnt(4)
	v_mfma_f32_16x16x32_bf16 v[148:151], v[240:243], v[80:83], v[148:151]
	v_mfma_f32_16x16x32_bf16 v[24:27], v[240:243], v[84:87], v[24:27]
	ds_read_b128 v[240:243], v212 offset:59264
	s_waitcnt lgkmcnt(4)
	v_mfma_f32_16x16x32_bf16 v[148:151], v[244:247], v[68:71], v[148:151]
	v_mfma_f32_16x16x32_bf16 v[24:27], v[244:247], v[72:75], v[24:27]
	ds_read_b128 v[244:247], v212 offset:59328
	s_waitcnt lgkmcnt(4)
	v_mfma_f32_16x16x32_bf16 v[148:151], v[228:231], v[60:63], v[148:151]
	v_mfma_f32_16x16x32_bf16 v[24:27], v[228:231], v[76:79], v[24:27]
	ds_read_b128 v[228:231], v212 offset:59392
	s_waitcnt lgkmcnt(4)
	v_mfma_f32_16x16x32_bf16 v[152:155], v[232:235], v[112:115], 0
	v_mfma_f32_16x16x32_bf16 v[28:31], v[232:235], v[124:127], 0
	ds_read_b128 v[232:235], v212 offset:59456
	s_waitcnt lgkmcnt(4)
	v_mfma_f32_16x16x32_bf16 v[152:155], v[236:239], v[116:119], v[152:155]
	v_mfma_f32_16x16x32_bf16 v[28:31], v[236:239], v[120:123], v[28:31]
	ds_read_b128 v[236:239], v212 offset:59520
	s_waitcnt lgkmcnt(4)
	v_mfma_f32_16x16x32_bf16 v[152:155], v[240:243], v[104:107], v[152:155]
	v_mfma_f32_16x16x32_bf16 v[28:31], v[240:243], v[108:111], v[28:31]
	ds_read_b128 v[240:243], v212 offset:59584
	s_waitcnt lgkmcnt(4)
	v_mfma_f32_16x16x32_bf16 v[152:155], v[244:247], v[96:99], v[152:155]
	v_mfma_f32_16x16x32_bf16 v[28:31], v[244:247], v[100:103], v[28:31]
	ds_read_b128 v[244:247], v215
	s_waitcnt lgkmcnt(4)
	v_mfma_f32_16x16x32_bf16 v[152:155], v[228:231], v[88:91], v[152:155]
	v_mfma_f32_16x16x32_bf16 v[28:31], v[228:231], v[92:95], v[28:31]
	ds_read_b128 v[228:231], v215 offset:64
	s_waitcnt lgkmcnt(4)
	v_mfma_f32_16x16x32_bf16 v[152:155], v[232:235], v[80:83], v[152:155]
	v_mfma_f32_16x16x32_bf16 v[28:31], v[232:235], v[84:87], v[28:31]
	ds_read_b128 v[232:235], v215 offset:128
	s_waitcnt lgkmcnt(4)
	v_mfma_f32_16x16x32_bf16 v[152:155], v[236:239], v[68:71], v[152:155]
	v_mfma_f32_16x16x32_bf16 v[28:31], v[236:239], v[72:75], v[28:31]
	ds_read_b128 v[236:239], v215 offset:192
	s_waitcnt lgkmcnt(4)
	v_mfma_f32_16x16x32_bf16 v[152:155], v[240:243], v[60:63], v[152:155]
	v_mfma_f32_16x16x32_bf16 v[28:31], v[240:243], v[76:79], v[28:31]
	ds_read_b128 v[240:243], v215 offset:256
	s_waitcnt lgkmcnt(4)
	v_mfma_f32_16x16x32_bf16 v[156:159], v[244:247], v[112:115], 0
	v_mfma_f32_16x16x32_bf16 v[32:35], v[244:247], v[124:127], 0
	ds_read_b128 v[244:247], v215 offset:320
	s_waitcnt lgkmcnt(4)
	v_mfma_f32_16x16x32_bf16 v[156:159], v[228:231], v[116:119], v[156:159]
	v_mfma_f32_16x16x32_bf16 v[32:35], v[228:231], v[120:123], v[32:35]
	ds_read_b128 v[228:231], v215 offset:384
	s_waitcnt lgkmcnt(4)
	v_mfma_f32_16x16x32_bf16 v[156:159], v[232:235], v[104:107], v[156:159]
	v_mfma_f32_16x16x32_bf16 v[32:35], v[232:235], v[108:111], v[32:35]
	ds_read_b128 v[232:235], v215 offset:448
	s_waitcnt lgkmcnt(4)
	v_mfma_f32_16x16x32_bf16 v[156:159], v[236:239], v[96:99], v[156:159]
	v_mfma_f32_16x16x32_bf16 v[32:35], v[236:239], v[100:103], v[32:35]
	ds_read_b128 v[236:239], v215 offset:8448
	s_waitcnt lgkmcnt(4)
	v_mfma_f32_16x16x32_bf16 v[156:159], v[240:243], v[88:91], v[156:159]
	v_mfma_f32_16x16x32_bf16 v[32:35], v[240:243], v[92:95], v[32:35]
	ds_read_b128 v[240:243], v215 offset:8512
	s_waitcnt lgkmcnt(4)
	v_mfma_f32_16x16x32_bf16 v[156:159], v[244:247], v[80:83], v[156:159]
	v_mfma_f32_16x16x32_bf16 v[32:35], v[244:247], v[84:87], v[32:35]
	ds_read_b128 v[244:247], v215 offset:8576
	s_waitcnt lgkmcnt(4)
	v_mfma_f32_16x16x32_bf16 v[156:159], v[228:231], v[68:71], v[156:159]
	v_mfma_f32_16x16x32_bf16 v[32:35], v[228:231], v[72:75], v[32:35]
	ds_read_b128 v[228:231], v215 offset:8640
	s_waitcnt lgkmcnt(4)
	v_mfma_f32_16x16x32_bf16 v[156:159], v[232:235], v[60:63], v[156:159]
	v_mfma_f32_16x16x32_bf16 v[32:35], v[232:235], v[76:79], v[32:35]
	ds_read_b128 v[232:235], v215 offset:8704
	s_waitcnt lgkmcnt(4)
	v_mfma_f32_16x16x32_bf16 v[160:163], v[236:239], v[112:115], 0
	v_mfma_f32_16x16x32_bf16 v[36:39], v[236:239], v[124:127], 0
	ds_read_b128 v[236:239], v215 offset:8768
	s_waitcnt lgkmcnt(4)
	v_mfma_f32_16x16x32_bf16 v[160:163], v[240:243], v[116:119], v[160:163]
	v_mfma_f32_16x16x32_bf16 v[36:39], v[240:243], v[120:123], v[36:39]
	ds_read_b128 v[240:243], v215 offset:8832
	s_waitcnt lgkmcnt(4)
	v_mfma_f32_16x16x32_bf16 v[160:163], v[244:247], v[104:107], v[160:163]
	v_mfma_f32_16x16x32_bf16 v[36:39], v[244:247], v[108:111], v[36:39]
	ds_read_b128 v[244:247], v215 offset:8896
	s_waitcnt lgkmcnt(4)
	v_mfma_f32_16x16x32_bf16 v[160:163], v[228:231], v[96:99], v[160:163]
	v_mfma_f32_16x16x32_bf16 v[36:39], v[228:231], v[100:103], v[36:39]
	ds_read_b128 v[228:231], v215 offset:16896
	s_waitcnt lgkmcnt(4)
	v_mfma_f32_16x16x32_bf16 v[160:163], v[232:235], v[88:91], v[160:163]
	v_mfma_f32_16x16x32_bf16 v[36:39], v[232:235], v[92:95], v[36:39]
	ds_read_b128 v[232:235], v215 offset:16960
	s_waitcnt lgkmcnt(4)
	v_mfma_f32_16x16x32_bf16 v[160:163], v[236:239], v[80:83], v[160:163]
	v_mfma_f32_16x16x32_bf16 v[36:39], v[236:239], v[84:87], v[36:39]
	ds_read_b128 v[236:239], v215 offset:17024
	s_waitcnt lgkmcnt(4)
	v_mfma_f32_16x16x32_bf16 v[160:163], v[240:243], v[68:71], v[160:163]
	v_mfma_f32_16x16x32_bf16 v[36:39], v[240:243], v[72:75], v[36:39]
	ds_read_b128 v[240:243], v215 offset:17088
	s_waitcnt lgkmcnt(4)
	v_mfma_f32_16x16x32_bf16 v[160:163], v[244:247], v[60:63], v[160:163]
	v_mfma_f32_16x16x32_bf16 v[36:39], v[244:247], v[76:79], v[36:39]
	ds_read_b128 v[244:247], v215 offset:17152
	s_waitcnt lgkmcnt(4)
	v_mfma_f32_16x16x32_bf16 v[164:167], v[228:231], v[112:115], 0
	v_mfma_f32_16x16x32_bf16 v[40:43], v[228:231], v[124:127], 0
	ds_read_b128 v[228:231], v215 offset:17216
	s_waitcnt lgkmcnt(4)
	v_mfma_f32_16x16x32_bf16 v[164:167], v[232:235], v[116:119], v[164:167]
	v_mfma_f32_16x16x32_bf16 v[40:43], v[232:235], v[120:123], v[40:43]
	ds_read_b128 v[232:235], v215 offset:17280
	s_waitcnt lgkmcnt(4)
	v_mfma_f32_16x16x32_bf16 v[164:167], v[236:239], v[104:107], v[164:167]
	v_mfma_f32_16x16x32_bf16 v[40:43], v[236:239], v[108:111], v[40:43]
	ds_read_b128 v[236:239], v215 offset:17344
	s_waitcnt lgkmcnt(4)
	v_mfma_f32_16x16x32_bf16 v[164:167], v[240:243], v[96:99], v[164:167]
	v_mfma_f32_16x16x32_bf16 v[40:43], v[240:243], v[100:103], v[40:43]
	ds_read_b128 v[240:243], v215 offset:25344
	s_waitcnt lgkmcnt(4)
	v_mfma_f32_16x16x32_bf16 v[164:167], v[244:247], v[88:91], v[164:167]
	v_mfma_f32_16x16x32_bf16 v[40:43], v[244:247], v[92:95], v[40:43]
	ds_read_b128 v[244:247], v215 offset:25408
	s_waitcnt lgkmcnt(4)
	v_mfma_f32_16x16x32_bf16 v[164:167], v[228:231], v[80:83], v[164:167]
	v_mfma_f32_16x16x32_bf16 v[40:43], v[228:231], v[84:87], v[40:43]
	ds_read_b128 v[228:231], v215 offset:25472
	s_waitcnt lgkmcnt(4)
	v_mfma_f32_16x16x32_bf16 v[164:167], v[232:235], v[68:71], v[164:167]
	v_mfma_f32_16x16x32_bf16 v[40:43], v[232:235], v[72:75], v[40:43]
	ds_read_b128 v[232:235], v215 offset:25536
	s_waitcnt lgkmcnt(4)
	v_mfma_f32_16x16x32_bf16 v[164:167], v[236:239], v[60:63], v[164:167]
	v_mfma_f32_16x16x32_bf16 v[40:43], v[236:239], v[76:79], v[40:43]
	ds_read_b128 v[236:239], v215 offset:25600
	s_waitcnt lgkmcnt(4)
	v_mfma_f32_16x16x32_bf16 v[168:171], v[240:243], v[112:115], 0
	v_mfma_f32_16x16x32_bf16 v[44:47], v[240:243], v[124:127], 0
	ds_read_b128 v[240:243], v215 offset:25664
	s_waitcnt lgkmcnt(4)
	v_mfma_f32_16x16x32_bf16 v[168:171], v[244:247], v[116:119], v[168:171]
	v_mfma_f32_16x16x32_bf16 v[44:47], v[244:247], v[120:123], v[44:47]
	ds_read_b128 v[244:247], v215 offset:25728
	s_waitcnt lgkmcnt(4)
	v_mfma_f32_16x16x32_bf16 v[168:171], v[228:231], v[104:107], v[168:171]
	v_mfma_f32_16x16x32_bf16 v[44:47], v[228:231], v[108:111], v[44:47]
	ds_read_b128 v[228:231], v215 offset:25792
	s_waitcnt lgkmcnt(4)
	v_mfma_f32_16x16x32_bf16 v[168:171], v[232:235], v[96:99], v[168:171]
	v_mfma_f32_16x16x32_bf16 v[44:47], v[232:235], v[100:103], v[44:47]
	ds_read_b128 v[232:235], v215 offset:33792
	s_waitcnt lgkmcnt(4)
	v_mfma_f32_16x16x32_bf16 v[168:171], v[236:239], v[88:91], v[168:171]
	v_mfma_f32_16x16x32_bf16 v[44:47], v[236:239], v[92:95], v[44:47]
	ds_read_b128 v[236:239], v215 offset:33856
	s_waitcnt lgkmcnt(4)
	v_mfma_f32_16x16x32_bf16 v[168:171], v[240:243], v[80:83], v[168:171]
	v_mfma_f32_16x16x32_bf16 v[44:47], v[240:243], v[84:87], v[44:47]
	ds_read_b128 v[240:243], v215 offset:33920
	s_waitcnt lgkmcnt(4)
	v_mfma_f32_16x16x32_bf16 v[168:171], v[244:247], v[68:71], v[168:171]
	v_mfma_f32_16x16x32_bf16 v[44:47], v[244:247], v[72:75], v[44:47]
	ds_read_b128 v[244:247], v215 offset:33984
	s_waitcnt lgkmcnt(4)
	v_mfma_f32_16x16x32_bf16 v[168:171], v[228:231], v[60:63], v[168:171]
	v_mfma_f32_16x16x32_bf16 v[44:47], v[228:231], v[76:79], v[44:47]
	ds_read_b128 v[228:231], v215 offset:34048
	s_waitcnt lgkmcnt(4)
	v_mfma_f32_16x16x32_bf16 v[172:175], v[232:235], v[112:115], 0
	v_mfma_f32_16x16x32_bf16 v[48:51], v[232:235], v[124:127], 0
	ds_read_b128 v[232:235], v215 offset:34112
	s_waitcnt lgkmcnt(4)
	v_mfma_f32_16x16x32_bf16 v[172:175], v[236:239], v[116:119], v[172:175]
	v_mfma_f32_16x16x32_bf16 v[48:51], v[236:239], v[120:123], v[48:51]
	ds_read_b128 v[236:239], v215 offset:34176
	s_waitcnt lgkmcnt(4)
	v_mfma_f32_16x16x32_bf16 v[172:175], v[240:243], v[104:107], v[172:175]
	v_mfma_f32_16x16x32_bf16 v[48:51], v[240:243], v[108:111], v[48:51]
	ds_read_b128 v[240:243], v215 offset:34240
	s_waitcnt lgkmcnt(4)
	v_mfma_f32_16x16x32_bf16 v[172:175], v[244:247], v[96:99], v[172:175]
	v_mfma_f32_16x16x32_bf16 v[48:51], v[244:247], v[100:103], v[48:51]
	ds_read_b128 v[244:247], v215 offset:42240
	s_waitcnt lgkmcnt(4)
	v_mfma_f32_16x16x32_bf16 v[172:175], v[228:231], v[88:91], v[172:175]
	v_mfma_f32_16x16x32_bf16 v[48:51], v[228:231], v[92:95], v[48:51]
	ds_read_b128 v[228:231], v215 offset:42304
	s_waitcnt lgkmcnt(4)
	v_mfma_f32_16x16x32_bf16 v[172:175], v[232:235], v[80:83], v[172:175]
	v_mfma_f32_16x16x32_bf16 v[48:51], v[232:235], v[84:87], v[48:51]
	ds_read_b128 v[232:235], v215 offset:42368
	s_waitcnt lgkmcnt(4)
	v_mfma_f32_16x16x32_bf16 v[172:175], v[236:239], v[68:71], v[172:175]
	v_mfma_f32_16x16x32_bf16 v[48:51], v[236:239], v[72:75], v[48:51]
	ds_read_b128 v[236:239], v215 offset:42432
	s_waitcnt lgkmcnt(4)
	v_mfma_f32_16x16x32_bf16 v[172:175], v[240:243], v[60:63], v[172:175]
	v_mfma_f32_16x16x32_bf16 v[48:51], v[240:243], v[76:79], v[48:51]
	ds_read_b128 v[240:243], v215 offset:42496
	s_waitcnt lgkmcnt(4)
	v_mfma_f32_16x16x32_bf16 v[176:179], v[244:247], v[112:115], 0
	v_mfma_f32_16x16x32_bf16 v[52:55], v[244:247], v[124:127], 0
	ds_read_b128 v[244:247], v215 offset:42560
	s_waitcnt lgkmcnt(4)
	v_mfma_f32_16x16x32_bf16 v[176:179], v[228:231], v[116:119], v[176:179]
	v_mfma_f32_16x16x32_bf16 v[52:55], v[228:231], v[120:123], v[52:55]
	ds_read_b128 v[228:231], v215 offset:42624
	s_waitcnt lgkmcnt(4)
	v_mfma_f32_16x16x32_bf16 v[176:179], v[232:235], v[104:107], v[176:179]
	v_mfma_f32_16x16x32_bf16 v[52:55], v[232:235], v[108:111], v[52:55]
	ds_read_b128 v[232:235], v215 offset:42688
	s_waitcnt lgkmcnt(4)
	v_mfma_f32_16x16x32_bf16 v[176:179], v[236:239], v[96:99], v[176:179]
	v_mfma_f32_16x16x32_bf16 v[52:55], v[236:239], v[100:103], v[52:55]
	ds_read_b128 v[236:239], v215 offset:50688
	s_waitcnt lgkmcnt(4)
	v_mfma_f32_16x16x32_bf16 v[176:179], v[240:243], v[88:91], v[176:179]
	v_mfma_f32_16x16x32_bf16 v[52:55], v[240:243], v[92:95], v[52:55]
	ds_read_b128 v[240:243], v215 offset:50752
	s_waitcnt lgkmcnt(4)
	v_mfma_f32_16x16x32_bf16 v[176:179], v[244:247], v[80:83], v[176:179]
	v_mfma_f32_16x16x32_bf16 v[52:55], v[244:247], v[84:87], v[52:55]
	ds_read_b128 v[244:247], v215 offset:50816
	s_waitcnt lgkmcnt(4)
	v_mfma_f32_16x16x32_bf16 v[176:179], v[228:231], v[68:71], v[176:179]
	v_mfma_f32_16x16x32_bf16 v[52:55], v[228:231], v[72:75], v[52:55]
	ds_read_b128 v[228:231], v215 offset:50880
	s_waitcnt lgkmcnt(4)
	v_mfma_f32_16x16x32_bf16 v[176:179], v[232:235], v[60:63], v[176:179]
	v_mfma_f32_16x16x32_bf16 v[52:55], v[232:235], v[76:79], v[52:55]
	ds_read_b128 v[232:235], v215 offset:50944
	s_waitcnt lgkmcnt(4)
	v_mfma_f32_16x16x32_bf16 v[180:183], v[236:239], v[112:115], 0
	v_mfma_f32_16x16x32_bf16 v[56:59], v[236:239], v[124:127], 0
	ds_read_b128 v[236:239], v215 offset:51008
	s_waitcnt lgkmcnt(4)
	v_mfma_f32_16x16x32_bf16 v[180:183], v[240:243], v[116:119], v[180:183]
	v_mfma_f32_16x16x32_bf16 v[56:59], v[240:243], v[120:123], v[56:59]
	ds_read_b128 v[240:243], v215 offset:51072
	s_waitcnt lgkmcnt(4)
	v_mfma_f32_16x16x32_bf16 v[180:183], v[244:247], v[104:107], v[180:183]
	v_mfma_f32_16x16x32_bf16 v[56:59], v[244:247], v[108:111], v[56:59]
	ds_read_b128 v[244:247], v215 offset:51136
	s_waitcnt lgkmcnt(4)
	v_mfma_f32_16x16x32_bf16 v[180:183], v[228:231], v[96:99], v[180:183]
	v_mfma_f32_16x16x32_bf16 v[56:59], v[228:231], v[100:103], v[56:59]
	ds_read_b128 v[228:231], v215 offset:59136
	s_waitcnt lgkmcnt(4)
	v_mfma_f32_16x16x32_bf16 v[180:183], v[232:235], v[88:91], v[180:183]
	v_mfma_f32_16x16x32_bf16 v[56:59], v[232:235], v[92:95], v[56:59]
	ds_read_b128 v[232:235], v215 offset:59200
	s_waitcnt lgkmcnt(4)
	v_mfma_f32_16x16x32_bf16 v[180:183], v[236:239], v[80:83], v[180:183]
	v_mfma_f32_16x16x32_bf16 v[56:59], v[236:239], v[84:87], v[56:59]
	ds_read_b128 v[236:239], v215 offset:59264
	s_waitcnt lgkmcnt(4)
	v_mfma_f32_16x16x32_bf16 v[180:183], v[240:243], v[68:71], v[180:183]
	v_mfma_f32_16x16x32_bf16 v[56:59], v[240:243], v[72:75], v[56:59]
	ds_read_b128 v[240:243], v215 offset:59328
	s_waitcnt lgkmcnt(4)
	v_mfma_f32_16x16x32_bf16 v[180:183], v[244:247], v[60:63], v[180:183]
	v_mfma_f32_16x16x32_bf16 v[56:59], v[244:247], v[76:79], v[56:59]
	ds_read_b128 v[244:247], v215 offset:59392
	s_waitcnt lgkmcnt(4)
	v_mfma_f32_16x16x32_bf16 v[224:227], v[228:231], v[112:115], 0
	v_mfma_f32_16x16x32_bf16 v[248:251], v[228:231], v[124:127], 0
	ds_read_b128 v[228:231], v215 offset:59456
	s_waitcnt lgkmcnt(4)
	v_mfma_f32_16x16x32_bf16 v[224:227], v[232:235], v[116:119], v[224:227]
	v_mfma_f32_16x16x32_bf16 v[248:251], v[232:235], v[120:123], v[248:251]
	ds_read_b128 v[232:235], v215 offset:59520
	s_waitcnt lgkmcnt(4)
	v_mfma_f32_16x16x32_bf16 v[224:227], v[236:239], v[104:107], v[224:227]
	v_mfma_f32_16x16x32_bf16 v[248:251], v[236:239], v[108:111], v[248:251]
	ds_read_b128 v[236:239], v215 offset:59584
	s_waitcnt lgkmcnt(4)
	v_mfma_f32_16x16x32_bf16 v[224:227], v[240:243], v[96:99], v[224:227]
	v_mfma_f32_16x16x32_bf16 v[248:251], v[240:243], v[100:103], v[248:251]
	s_waitcnt lgkmcnt(3)
	v_mfma_f32_16x16x32_bf16 v[224:227], v[244:247], v[88:91], v[224:227]
	v_mfma_f32_16x16x32_bf16 v[248:251], v[244:247], v[92:95], v[248:251]
	s_waitcnt lgkmcnt(2)
	v_mfma_f32_16x16x32_bf16 v[224:227], v[228:231], v[80:83], v[224:227]
	v_mfma_f32_16x16x32_bf16 v[248:251], v[228:231], v[84:87], v[248:251]
	s_waitcnt lgkmcnt(1)
	v_mfma_f32_16x16x32_bf16 v[224:227], v[232:235], v[68:71], v[224:227]
	v_mfma_f32_16x16x32_bf16 v[248:251], v[232:235], v[72:75], v[248:251]
	s_waitcnt lgkmcnt(0)
	v_mfma_f32_16x16x32_bf16 v[68:71], v[236:239], v[60:63], v[224:227]
	v_mfma_f32_16x16x32_bf16 v[60:63], v[236:239], v[76:79], v[248:251]
	s_barrier
	v_or_b32_e32 v252, s7, v187
	v_lshlrev_b32_e32 v252, 12, v252
	v_add_u32_e32 v252, v252, v190
	s_lshl_b32 s14, s6, 1
	s_add_u32 s14, s12, s14
	s_addc_u32 s15, s13, 0
	global_load_dwordx4 v[224:227], v252, s[14:15]
	s_add_u32 s14, s14, 0x10000
	s_addc_u32 s15, s15, 0
	global_load_dwordx4 v[228:231], v252, s[14:15]
	s_add_u32 s14, s14, 0x10000
	s_addc_u32 s15, s15, 0
	global_load_dwordx4 v[232:235], v252, s[14:15]
	s_add_u32 s14, s14, 0x10000
	s_addc_u32 s15, s15, 0
	global_load_dwordx4 v[236:239], v252, s[14:15]
	s_add_u32 s14, s14, 0x10000
	s_addc_u32 s15, s15, 0
	global_load_dwordx4 v[240:243], v252, s[14:15]
	s_add_u32 s14, s14, 0x10000
	s_addc_u32 s15, s15, 0
	global_load_dwordx4 v[244:247], v252, s[14:15]
	s_add_u32 s14, s14, 0x10000
	s_addc_u32 s15, s15, 0
	global_load_dwordx4 v[248:251], v252, s[14:15]
	s_add_u32 s14, s14, 0x10000
	s_addc_u32 s15, s15, 0
	v_max_f32_e32 v72, v65, v65
	v_max_f32_e32 v73, v64, v64
	v_max_f32_e32 v72, v73, v72
	v_max3_f32 v72, v72, v66, v67
	v_max3_f32 v72, v72, v128, v129
	v_max3_f32 v72, v72, v130, v131
	v_max3_f32 v72, v72, v132, v133
	v_max3_f32 v72, v72, v134, v135
	v_max3_f32 v72, v72, v136, v137
	v_max3_f32 v72, v72, v138, v139
	v_max3_f32 v72, v72, v140, v141
	v_max3_f32 v72, v72, v142, v143
	v_max3_f32 v72, v72, v144, v145
	v_max3_f32 v72, v72, v146, v147
	v_max3_f32 v72, v72, v148, v149
	v_max3_f32 v72, v72, v150, v151
	v_max3_f32 v72, v72, v152, v153
	v_max3_f32 v72, v72, v154, v155
	v_max3_f32 v72, v72, v156, v157
	v_max3_f32 v72, v72, v158, v159
	v_max3_f32 v72, v72, v160, v161
	v_max3_f32 v72, v72, v162, v163
	v_max3_f32 v72, v72, v164, v165
	v_max3_f32 v72, v72, v166, v167
	v_max3_f32 v72, v72, v168, v169
	v_max3_f32 v72, v72, v170, v171
	v_max3_f32 v72, v72, v172, v173
	v_max3_f32 v72, v72, v174, v175
	v_max3_f32 v72, v72, v176, v177
	v_max3_f32 v72, v72, v178, v179
	v_max3_f32 v72, v72, v180, v181
	v_max3_f32 v72, v72, v182, v183
	v_max3_f32 v72, v72, v68, v69
	v_max3_f32 v72, v72, v70, v71
	ds_bpermute_b32 v73, v198, v72
	s_waitcnt lgkmcnt(0)
	v_max_f32_e32 v73, v73, v73
	v_max_f32_e32 v72, v72, v73
	ds_bpermute_b32 v73, v199, v72
	s_waitcnt lgkmcnt(0)
	v_max_f32_e32 v73, v73, v73
	v_max_f32_e32 v223, v72, v73
	v_sub_f32_e32 v64, v64, v223
	v_mul_f32_e32 v64, 0x3d800000, v64
	v_sub_f32_e32 v65, v65, v223
	v_mul_f32_e32 v64, 0x3fb8aa3b, v64
	v_mul_f32_e32 v65, 0x3d800000, v65
	v_sub_f32_e32 v66, v66, v223
	v_exp_f32_e32 v64, v64
	v_mul_f32_e32 v65, 0x3fb8aa3b, v65
	v_mul_f32_e32 v66, 0x3d800000, v66
	v_sub_f32_e32 v67, v67, v223
	v_exp_f32_e32 v65, v65
	v_mul_f32_e32 v66, 0x3fb8aa3b, v66
	v_mul_f32_e32 v67, 0x3d800000, v67
	v_exp_f32_e32 v66, v66
	v_mul_f32_e32 v67, 0x3fb8aa3b, v67
	v_exp_f32_e32 v67, v67
	v_add_f32_e32 v72, 0, v64
	v_add_f32_e32 v72, v65, v72
	v_add_f32_e32 v72, v66, v72
	v_add_f32_e32 v73, v67, v72
	v_sub_f32_e32 v72, v128, v223
	v_mul_f32_e32 v72, 0x3d800000, v72
	v_mul_f32_e32 v72, 0x3fb8aa3b, v72
	v_exp_f32_e32 v72, v72
	v_sub_f32_e32 v95, v150, v223
	v_mul_f32_e32 v95, 0x3d800000, v95
	v_mul_f32_e32 v95, 0x3fb8aa3b, v95
	v_add_f32_e32 v74, v72, v73
	v_sub_f32_e32 v73, v129, v223
	v_mul_f32_e32 v73, 0x3d800000, v73
	v_mul_f32_e32 v73, 0x3fb8aa3b, v73
	v_exp_f32_e32 v73, v73
	v_exp_f32_e32 v96, v95
	v_sub_f32_e32 v95, v151, v223
	v_mul_f32_e32 v95, 0x3d800000, v95
	v_add_f32_e32 v75, v73, v74
	v_sub_f32_e32 v74, v130, v223
	v_mul_f32_e32 v74, 0x3d800000, v74
	v_mul_f32_e32 v74, 0x3fb8aa3b, v74
	v_exp_f32_e32 v74, v74
	v_mul_f32_e32 v95, 0x3fb8aa3b, v95
	v_exp_f32_e32 v97, v95
	v_sub_f32_e32 v95, v152, v223
	v_add_f32_e32 v76, v74, v75
	v_sub_f32_e32 v75, v131, v223
	v_mul_f32_e32 v75, 0x3d800000, v75
	v_mul_f32_e32 v75, 0x3fb8aa3b, v75
	v_exp_f32_e32 v75, v75
	v_mul_f32_e32 v95, 0x3d800000, v95
	v_mul_f32_e32 v95, 0x3fb8aa3b, v95
	v_exp_f32_e32 v99, v95
	v_add_f32_e32 v77, v75, v76
	v_sub_f32_e32 v76, v132, v223
	v_mul_f32_e32 v76, 0x3d800000, v76
	v_mul_f32_e32 v76, 0x3fb8aa3b, v76
	v_exp_f32_e32 v76, v76
	v_sub_f32_e32 v95, v153, v223
	v_mul_f32_e32 v95, 0x3d800000, v95
	v_mul_f32_e32 v95, 0x3fb8aa3b, v95
	v_add_f32_e32 v78, v76, v77
	v_sub_f32_e32 v77, v133, v223
	v_mul_f32_e32 v77, 0x3d800000, v77
	v_mul_f32_e32 v77, 0x3fb8aa3b, v77
	v_exp_f32_e32 v77, v77
	v_exp_f32_e32 v101, v95
	v_sub_f32_e32 v95, v154, v223
	v_mul_f32_e32 v95, 0x3d800000, v95
	v_add_f32_e32 v79, v77, v78
	v_sub_f32_e32 v78, v134, v223
	v_mul_f32_e32 v78, 0x3d800000, v78
	v_mul_f32_e32 v78, 0x3fb8aa3b, v78
	v_exp_f32_e32 v78, v78
	v_mul_f32_e32 v95, 0x3fb8aa3b, v95
	v_exp_f32_e32 v104, v95
	v_sub_f32_e32 v95, v155, v223
	v_add_f32_e32 v80, v78, v79
	v_sub_f32_e32 v79, v135, v223
	v_mul_f32_e32 v79, 0x3d800000, v79
	v_mul_f32_e32 v79, 0x3fb8aa3b, v79
	v_exp_f32_e32 v79, v79
	v_mul_f32_e32 v95, 0x3d800000, v95
	v_mul_f32_e32 v95, 0x3fb8aa3b, v95
	v_exp_f32_e32 v105, v95
	v_add_f32_e32 v81, v79, v80
	v_sub_f32_e32 v80, v136, v223
	v_mul_f32_e32 v80, 0x3d800000, v80
	v_mul_f32_e32 v80, 0x3fb8aa3b, v80
	v_exp_f32_e32 v80, v80
	v_sub_f32_e32 v95, v156, v223
	v_mul_f32_e32 v95, 0x3d800000, v95
	v_mul_f32_e32 v95, 0x3fb8aa3b, v95
	v_add_f32_e32 v82, v80, v81
	v_sub_f32_e32 v81, v137, v223
	v_mul_f32_e32 v81, 0x3d800000, v81
	v_mul_f32_e32 v81, 0x3fb8aa3b, v81
	v_exp_f32_e32 v81, v81
	v_exp_f32_e32 v107, v95
	v_sub_f32_e32 v95, v157, v223
	v_mul_f32_e32 v95, 0x3d800000, v95
	v_add_f32_e32 v83, v81, v82
	v_sub_f32_e32 v82, v138, v223
	v_mul_f32_e32 v82, 0x3d800000, v82
	v_mul_f32_e32 v82, 0x3fb8aa3b, v82
	v_exp_f32_e32 v82, v82
	v_mul_f32_e32 v95, 0x3fb8aa3b, v95
	v_exp_f32_e32 v109, v95
	v_sub_f32_e32 v95, v158, v223
	v_add_f32_e32 v84, v82, v83
	v_sub_f32_e32 v83, v139, v223
	v_mul_f32_e32 v83, 0x3d800000, v83
	v_mul_f32_e32 v83, 0x3fb8aa3b, v83
	v_exp_f32_e32 v83, v83
	v_mul_f32_e32 v95, 0x3d800000, v95
	v_mul_f32_e32 v95, 0x3fb8aa3b, v95
	v_exp_f32_e32 v112, v95
	v_add_f32_e32 v85, v83, v84
	v_sub_f32_e32 v84, v140, v223
	v_mul_f32_e32 v84, 0x3d800000, v84
	v_mul_f32_e32 v84, 0x3fb8aa3b, v84
	v_exp_f32_e32 v84, v84
	v_sub_f32_e32 v95, v159, v223
	v_mul_f32_e32 v95, 0x3d800000, v95
	v_mul_f32_e32 v95, 0x3fb8aa3b, v95
	v_add_f32_e32 v86, v84, v85
	v_sub_f32_e32 v85, v141, v223
	v_mul_f32_e32 v85, 0x3d800000, v85
	v_mul_f32_e32 v85, 0x3fb8aa3b, v85
	v_exp_f32_e32 v85, v85
	v_exp_f32_e32 v113, v95
	v_sub_f32_e32 v116, v171, v223
	v_mul_f32_e32 v116, 0x3d800000, v116
	v_add_f32_e32 v87, v85, v86
	v_sub_f32_e32 v86, v142, v223
	v_mul_f32_e32 v86, 0x3d800000, v86
	v_mul_f32_e32 v86, 0x3fb8aa3b, v86
	v_exp_f32_e32 v86, v86
	v_mul_f32_e32 v116, 0x3fb8aa3b, v116
	v_exp_f32_e32 v116, v116
	v_sub_f32_e32 v118, v173, v223
	v_add_f32_e32 v88, v86, v87
	v_sub_f32_e32 v87, v143, v223
	v_mul_f32_e32 v87, 0x3d800000, v87
	v_mul_f32_e32 v87, 0x3fb8aa3b, v87
	v_exp_f32_e32 v87, v87
	v_mul_f32_e32 v118, 0x3d800000, v118
	v_mul_f32_e32 v118, 0x3fb8aa3b, v118
	v_exp_f32_e32 v118, v118
	v_add_f32_e32 v89, v87, v88
	v_sub_f32_e32 v88, v144, v223
	v_mul_f32_e32 v88, 0x3d800000, v88
	v_mul_f32_e32 v88, 0x3fb8aa3b, v88
	v_exp_f32_e32 v88, v88
	v_sub_f32_e32 v120, v175, v223
	v_mul_f32_e32 v120, 0x3d800000, v120
	v_mul_f32_e32 v120, 0x3fb8aa3b, v120
	v_add_f32_e32 v90, v88, v89
	v_sub_f32_e32 v89, v145, v223
	v_mul_f32_e32 v89, 0x3d800000, v89
	v_mul_f32_e32 v89, 0x3fb8aa3b, v89
	v_exp_f32_e32 v89, v89
	v_exp_f32_e32 v120, v120
	v_sub_f32_e32 v122, v177, v223
	v_mul_f32_e32 v122, 0x3d800000, v122
	v_add_f32_e32 v91, v89, v90
	v_sub_f32_e32 v90, v146, v223
	v_mul_f32_e32 v90, 0x3d800000, v90
	v_mul_f32_e32 v90, 0x3fb8aa3b, v90
	v_exp_f32_e32 v90, v90
	v_mul_f32_e32 v122, 0x3fb8aa3b, v122
	v_exp_f32_e32 v122, v122
	v_sub_f32_e32 v124, v179, v223
	v_add_f32_e32 v92, v90, v91
	v_sub_f32_e32 v91, v147, v223
	v_mul_f32_e32 v91, 0x3d800000, v91
	v_mul_f32_e32 v91, 0x3fb8aa3b, v91
	v_exp_f32_e32 v91, v91
	v_mul_f32_e32 v124, 0x3d800000, v124
	v_mul_f32_e32 v124, 0x3fb8aa3b, v124
	v_exp_f32_e32 v124, v124
	v_add_f32_e32 v93, v91, v92
	v_sub_f32_e32 v92, v148, v223
	v_mul_f32_e32 v92, 0x3d800000, v92
	v_mul_f32_e32 v92, 0x3fb8aa3b, v92
	v_exp_f32_e32 v92, v92
	v_sub_f32_e32 v126, v181, v223
	v_mul_f32_e32 v126, 0x3d800000, v126
	v_mul_f32_e32 v126, 0x3fb8aa3b, v126
	v_add_f32_e32 v94, v92, v93
	v_sub_f32_e32 v93, v149, v223
	v_mul_f32_e32 v93, 0x3d800000, v93
	v_mul_f32_e32 v93, 0x3fb8aa3b, v93
	v_exp_f32_e32 v93, v93
	v_exp_f32_e32 v126, v126
	v_sub_f32_e32 v68, v68, v223
	v_mul_f32_e32 v68, 0x3d800000, v68
	v_add_f32_e32 v94, v93, v94
	v_add_f32_e32 v94, v96, v94
	v_add_f32_e32 v94, v97, v94
	v_add_f32_e32 v94, v99, v94
	v_add_f32_e32 v94, v101, v94
	v_add_f32_e32 v94, v104, v94
	v_add_f32_e32 v94, v105, v94
	v_add_f32_e32 v94, v107, v94
	v_add_f32_e32 v94, v109, v94
	v_add_f32_e32 v94, v112, v94
	v_add_f32_e32 v95, v113, v94
	v_sub_f32_e32 v94, v160, v223
	v_mul_f32_e32 v94, 0x3d800000, v94
	v_mul_f32_e32 v94, 0x3fb8aa3b, v94
	v_exp_f32_e32 v94, v94
	v_sub_f32_e32 v69, v69, v223
	v_mul_f32_e32 v68, 0x3fb8aa3b, v68
	v_mul_f32_e32 v69, 0x3d800000, v69
	v_add_f32_e32 v98, v94, v95
	v_sub_f32_e32 v95, v161, v223
	v_mul_f32_e32 v95, 0x3d800000, v95
	v_mul_f32_e32 v95, 0x3fb8aa3b, v95
	v_exp_f32_e32 v95, v95
	v_sub_f32_e32 v70, v70, v223
	v_exp_f32_e32 v68, v68
	v_mul_f32_e32 v69, 0x3fb8aa3b, v69
	v_add_f32_e32 v100, v95, v98
	v_sub_f32_e32 v98, v162, v223
	v_mul_f32_e32 v98, 0x3d800000, v98
	v_mul_f32_e32 v98, 0x3fb8aa3b, v98
	v_exp_f32_e32 v98, v98
	v_mul_f32_e32 v70, 0x3d800000, v70
	v_sub_f32_e32 v71, v71, v223
	v_exp_f32_e32 v69, v69
	v_add_f32_e32 v102, v98, v100
	v_sub_f32_e32 v100, v163, v223
	v_mul_f32_e32 v100, 0x3d800000, v100
	v_mul_f32_e32 v100, 0x3fb8aa3b, v100
	v_exp_f32_e32 v100, v100
	v_mul_f32_e32 v70, 0x3fb8aa3b, v70
	v_mul_f32_e32 v71, 0x3d800000, v71
	v_exp_f32_e32 v70, v70
	v_add_f32_e32 v103, v100, v102
	v_sub_f32_e32 v102, v164, v223
	v_mul_f32_e32 v102, 0x3d800000, v102
	v_mul_f32_e32 v102, 0x3fb8aa3b, v102
	v_exp_f32_e32 v102, v102
	v_mul_f32_e32 v71, 0x3fb8aa3b, v71
	v_exp_f32_e32 v71, v71
	v_add_f32_e32 v106, v102, v103
	v_sub_f32_e32 v103, v165, v223
	v_mul_f32_e32 v103, 0x3d800000, v103
	v_mul_f32_e32 v103, 0x3fb8aa3b, v103
	v_exp_f32_e32 v103, v103
	s_nop 0
	v_add_f32_e32 v108, v103, v106
	v_sub_f32_e32 v106, v166, v223
	v_mul_f32_e32 v106, 0x3d800000, v106
	v_mul_f32_e32 v106, 0x3fb8aa3b, v106
	v_exp_f32_e32 v106, v106
	s_nop 0
	v_add_f32_e32 v110, v106, v108
	v_sub_f32_e32 v108, v167, v223
	v_mul_f32_e32 v108, 0x3d800000, v108
	v_mul_f32_e32 v108, 0x3fb8aa3b, v108
	v_exp_f32_e32 v108, v108
	s_nop 0
	v_add_f32_e32 v111, v108, v110
	v_sub_f32_e32 v110, v168, v223
	v_mul_f32_e32 v110, 0x3d800000, v110
	v_mul_f32_e32 v110, 0x3fb8aa3b, v110
	v_exp_f32_e32 v110, v110
	s_nop 0
	v_add_f32_e32 v114, v110, v111
	v_sub_f32_e32 v111, v169, v223
	v_mul_f32_e32 v111, 0x3d800000, v111
	v_mul_f32_e32 v111, 0x3fb8aa3b, v111
	v_exp_f32_e32 v111, v111
	s_nop 0
	v_add_f32_e32 v115, v111, v114
	v_sub_f32_e32 v114, v170, v223
	v_mul_f32_e32 v114, 0x3d800000, v114
	v_mul_f32_e32 v114, 0x3fb8aa3b, v114
	v_exp_f32_e32 v114, v114
	s_nop 0
	v_add_f32_e32 v115, v114, v115
	v_add_f32_e32 v117, v116, v115
	v_sub_f32_e32 v115, v172, v223
	v_mul_f32_e32 v115, 0x3d800000, v115
	v_mul_f32_e32 v115, 0x3fb8aa3b, v115
	v_exp_f32_e32 v115, v115
	s_nop 0
	v_add_f32_e32 v117, v115, v117
	v_add_f32_e32 v119, v118, v117
	v_sub_f32_e32 v117, v174, v223
	v_mul_f32_e32 v117, 0x3d800000, v117
	v_mul_f32_e32 v117, 0x3fb8aa3b, v117
	v_exp_f32_e32 v117, v117
	s_nop 0
	v_add_f32_e32 v119, v117, v119
	v_add_f32_e32 v121, v120, v119
	v_sub_f32_e32 v119, v176, v223
	v_mul_f32_e32 v119, 0x3d800000, v119
	v_mul_f32_e32 v119, 0x3fb8aa3b, v119
	v_exp_f32_e32 v119, v119
	s_nop 0
	v_add_f32_e32 v121, v119, v121
	v_add_f32_e32 v123, v122, v121
	v_sub_f32_e32 v121, v178, v223
	v_mul_f32_e32 v121, 0x3d800000, v121
	v_mul_f32_e32 v121, 0x3fb8aa3b, v121
	v_exp_f32_e32 v121, v121
	s_nop 0
	v_add_f32_e32 v123, v121, v123
	v_add_f32_e32 v125, v124, v123
	v_sub_f32_e32 v123, v180, v223
	v_mul_f32_e32 v123, 0x3d800000, v123
	v_mul_f32_e32 v123, 0x3fb8aa3b, v123
	v_exp_f32_e32 v123, v123
	s_nop 0
	v_add_f32_e32 v125, v123, v125
	v_add_f32_e32 v127, v126, v125
	v_sub_f32_e32 v125, v182, v223
	v_mul_f32_e32 v125, 0x3d800000, v125
	v_mul_f32_e32 v125, 0x3fb8aa3b, v125
	v_exp_f32_e32 v125, v125
	s_nop 0
	v_add_f32_e32 v128, v125, v127
	v_sub_f32_e32 v127, v183, v223
	v_mul_f32_e32 v127, 0x3d800000, v127
	v_mul_f32_e32 v127, 0x3fb8aa3b, v127
	v_exp_f32_e32 v127, v127
	s_nop 0
	v_add_f32_e32 v128, v127, v128
	v_add_f32_e32 v128, v68, v128
	v_add_f32_e32 v128, v69, v128
	v_add_f32_e32 v128, v70, v128
	v_add_f32_e32 v128, v71, v128
	ds_bpermute_b32 v129, v198, v128
	s_waitcnt lgkmcnt(0)
	v_add_f32_e32 v152, v128, v129
	v_max_f32_e32 v128, v1, v1
	v_max_f32_e32 v129, v0, v0
	v_max_f32_e32 v128, v129, v128
	v_max3_f32 v128, v128, v2, v3
	v_max3_f32 v128, v128, v4, v5
	v_max3_f32 v128, v128, v6, v7
	v_max3_f32 v128, v128, v8, v9
	v_max3_f32 v128, v128, v10, v11
	v_max3_f32 v128, v128, v12, v13
	v_max3_f32 v128, v128, v14, v15
	v_max3_f32 v128, v128, v16, v17
	v_max3_f32 v128, v128, v18, v19
	v_max3_f32 v128, v128, v20, v21
	v_max3_f32 v128, v128, v22, v23
	v_max3_f32 v128, v128, v24, v25
	v_max3_f32 v128, v128, v26, v27
	v_max3_f32 v128, v128, v28, v29
	v_max3_f32 v128, v128, v30, v31
	v_max3_f32 v128, v128, v32, v33
	v_max3_f32 v128, v128, v34, v35
	v_max3_f32 v128, v128, v36, v37
	v_max3_f32 v128, v128, v38, v39
	v_max3_f32 v128, v128, v40, v41
	v_max3_f32 v128, v128, v42, v43
	v_max3_f32 v128, v128, v44, v45
	v_max3_f32 v128, v128, v46, v47
	v_max3_f32 v128, v128, v48, v49
	v_max3_f32 v128, v128, v50, v51
	v_max3_f32 v128, v128, v52, v53
	v_max3_f32 v128, v128, v54, v55
	v_max3_f32 v128, v128, v56, v57
	v_max3_f32 v128, v128, v58, v59
	v_max3_f32 v128, v128, v60, v61
	v_max3_f32 v128, v128, v62, v63
	ds_bpermute_b32 v129, v198, v128
	ds_bpermute_b32 v153, v199, v152
	s_waitcnt lgkmcnt(1)
	v_max_f32_e32 v129, v129, v129
	v_max_f32_e32 v128, v128, v129
	ds_bpermute_b32 v129, v199, v128
	s_waitcnt lgkmcnt(0)
	v_max_f32_e32 v129, v129, v129
	v_max_f32_e32 v154, v128, v129
	v_sub_f32_e32 v1, v1, v154
	v_mul_f32_e32 v1, 0x3d800000, v1
	v_mul_f32_e32 v1, 0x3fb8aa3b, v1
	v_exp_f32_e32 v130, v1
	v_sub_f32_e32 v1, v2, v154
	v_mul_f32_e32 v1, 0x3d800000, v1
	v_mul_f32_e32 v1, 0x3fb8aa3b, v1
	v_exp_f32_e32 v129, v1
	v_sub_f32_e32 v1, v3, v154
	v_mul_f32_e32 v1, 0x3d800000, v1
	v_mul_f32_e32 v1, 0x3fb8aa3b, v1
	v_exp_f32_e32 v131, v1
	v_sub_f32_e32 v1, v4, v154
	v_mul_f32_e32 v1, 0x3d800000, v1
	v_mul_f32_e32 v1, 0x3fb8aa3b, v1
	v_exp_f32_e32 v132, v1
	v_sub_f32_e32 v1, v5, v154
	v_mul_f32_e32 v1, 0x3d800000, v1
	v_mul_f32_e32 v1, 0x3fb8aa3b, v1
	v_exp_f32_e32 v133, v1
	v_sub_f32_e32 v1, v6, v154
	v_mul_f32_e32 v1, 0x3d800000, v1
	v_mul_f32_e32 v1, 0x3fb8aa3b, v1
	v_exp_f32_e32 v134, v1
	v_sub_f32_e32 v1, v7, v154
	v_mul_f32_e32 v1, 0x3d800000, v1
	v_mul_f32_e32 v1, 0x3fb8aa3b, v1
	v_exp_f32_e32 v135, v1
	v_sub_f32_e32 v1, v8, v154
	v_mul_f32_e32 v1, 0x3d800000, v1
	v_mul_f32_e32 v1, 0x3fb8aa3b, v1
	v_exp_f32_e32 v136, v1
	v_sub_f32_e32 v1, v9, v154
	v_mul_f32_e32 v1, 0x3d800000, v1
	v_mul_f32_e32 v1, 0x3fb8aa3b, v1
	v_exp_f32_e32 v138, v1
	v_sub_f32_e32 v1, v10, v154
	v_mul_f32_e32 v1, 0x3d800000, v1
	v_mul_f32_e32 v1, 0x3fb8aa3b, v1
	v_exp_f32_e32 v137, v1
	v_sub_f32_e32 v1, v11, v154
	v_mul_f32_e32 v1, 0x3d800000, v1
	v_mul_f32_e32 v1, 0x3fb8aa3b, v1
	v_exp_f32_e32 v139, v1
	v_sub_f32_e32 v1, v12, v154
	v_mul_f32_e32 v1, 0x3d800000, v1
	v_mul_f32_e32 v1, 0x3fb8aa3b, v1
	v_exp_f32_e32 v140, v1
	v_sub_f32_e32 v1, v13, v154
	v_mul_f32_e32 v1, 0x3d800000, v1
	v_mul_f32_e32 v1, 0x3fb8aa3b, v1
	v_exp_f32_e32 v141, v1
	v_sub_f32_e32 v1, v14, v154
	v_mul_f32_e32 v1, 0x3d800000, v1
	v_mul_f32_e32 v1, 0x3fb8aa3b, v1
	v_exp_f32_e32 v142, v1
	v_sub_f32_e32 v1, v15, v154
	v_mul_f32_e32 v1, 0x3d800000, v1
	v_mul_f32_e32 v1, 0x3fb8aa3b, v1
	v_exp_f32_e32 v143, v1
	v_sub_f32_e32 v1, v16, v154
	v_mul_f32_e32 v1, 0x3d800000, v1
	v_mul_f32_e32 v1, 0x3fb8aa3b, v1
	v_exp_f32_e32 v144, v1
	v_sub_f32_e32 v1, v17, v154
	v_mul_f32_e32 v1, 0x3d800000, v1
	v_mul_f32_e32 v1, 0x3fb8aa3b, v1
	v_exp_f32_e32 v146, v1
	v_sub_f32_e32 v1, v18, v154
	v_mul_f32_e32 v1, 0x3d800000, v1
	v_mul_f32_e32 v1, 0x3fb8aa3b, v1
	v_exp_f32_e32 v145, v1
	v_sub_f32_e32 v1, v19, v154
	v_mul_f32_e32 v1, 0x3d800000, v1
	v_mul_f32_e32 v1, 0x3fb8aa3b, v1
	v_exp_f32_e32 v147, v1
	v_sub_f32_e32 v1, v20, v154
	v_mul_f32_e32 v1, 0x3d800000, v1
	v_mul_f32_e32 v1, 0x3fb8aa3b, v1
	v_exp_f32_e32 v148, v1
	v_sub_f32_e32 v1, v21, v154
	v_mul_f32_e32 v1, 0x3d800000, v1
	v_mul_f32_e32 v1, 0x3fb8aa3b, v1
	v_exp_f32_e32 v149, v1
	v_sub_f32_e32 v1, v22, v154
	v_mul_f32_e32 v1, 0x3d800000, v1
	v_mul_f32_e32 v1, 0x3fb8aa3b, v1
	v_exp_f32_e32 v150, v1
	v_sub_f32_e32 v1, v23, v154
	v_mul_f32_e32 v1, 0x3d800000, v1
	v_mul_f32_e32 v1, 0x3fb8aa3b, v1
	v_exp_f32_e32 v151, v1
	v_sub_f32_e32 v1, v24, v154
	v_mul_f32_e32 v1, 0x3d800000, v1
	v_mul_f32_e32 v1, 0x3fb8aa3b, v1
	v_exp_f32_e32 v156, v1
	v_sub_f32_e32 v1, v25, v154
	v_mul_f32_e32 v1, 0x3d800000, v1
	v_mul_f32_e32 v1, 0x3fb8aa3b, v1
	v_exp_f32_e32 v158, v1
	v_sub_f32_e32 v1, v26, v154
	v_mul_f32_e32 v1, 0x3d800000, v1
	v_mul_f32_e32 v1, 0x3fb8aa3b, v1
	v_exp_f32_e32 v157, v1
	v_sub_f32_e32 v1, v27, v154
	v_mul_f32_e32 v1, 0x3d800000, v1
	v_mul_f32_e32 v1, 0x3fb8aa3b, v1
	v_exp_f32_e32 v27, v1
	v_sub_f32_e32 v1, v28, v154
	v_mul_f32_e32 v1, 0x3d800000, v1
	v_mul_f32_e32 v1, 0x3fb8aa3b, v1
	v_exp_f32_e32 v28, v1
	v_sub_f32_e32 v1, v29, v154
	v_mul_f32_e32 v1, 0x3d800000, v1
	v_mul_f32_e32 v1, 0x3fb8aa3b, v1
	v_exp_f32_e32 v29, v1
	v_sub_f32_e32 v1, v30, v154
	v_mul_f32_e32 v1, 0x3d800000, v1
	v_mul_f32_e32 v1, 0x3fb8aa3b, v1
	v_exp_f32_e32 v30, v1
	v_sub_f32_e32 v1, v31, v154
	v_mul_f32_e32 v1, 0x3d800000, v1
	v_mul_f32_e32 v1, 0x3fb8aa3b, v1
	v_exp_f32_e32 v31, v1
	v_sub_f32_e32 v1, v32, v154
	v_mul_f32_e32 v1, 0x3d800000, v1
	v_mul_f32_e32 v1, 0x3fb8aa3b, v1
	v_exp_f32_e32 v32, v1
	v_sub_f32_e32 v1, v33, v154
	v_mul_f32_e32 v1, 0x3d800000, v1
	v_mul_f32_e32 v1, 0x3fb8aa3b, v1
	v_exp_f32_e32 v159, v1
	v_sub_f32_e32 v1, v34, v154
	v_mul_f32_e32 v1, 0x3d800000, v1
	v_mul_f32_e32 v1, 0x3fb8aa3b, v1
	v_exp_f32_e32 v33, v1
	v_sub_f32_e32 v1, v35, v154
	v_mul_f32_e32 v1, 0x3d800000, v1
	v_mul_f32_e32 v1, 0x3fb8aa3b, v1
	v_exp_f32_e32 v34, v1
	v_sub_f32_e32 v1, v36, v154
	v_mul_f32_e32 v1, 0x3d800000, v1
	v_mul_f32_e32 v1, 0x3fb8aa3b, v1
	v_exp_f32_e32 v35, v1
	v_sub_f32_e32 v1, v37, v154
	v_mul_f32_e32 v1, 0x3d800000, v1
	v_mul_f32_e32 v1, 0x3fb8aa3b, v1
	v_exp_f32_e32 v36, v1
	v_sub_f32_e32 v1, v38, v154
	v_mul_f32_e32 v1, 0x3d800000, v1
	v_mul_f32_e32 v1, 0x3fb8aa3b, v1
	v_exp_f32_e32 v37, v1
	v_sub_f32_e32 v1, v39, v154
	v_mul_f32_e32 v1, 0x3d800000, v1
	v_mul_f32_e32 v1, 0x3fb8aa3b, v1
	v_exp_f32_e32 v38, v1
	v_sub_f32_e32 v1, v40, v154
	v_mul_f32_e32 v1, 0x3d800000, v1
	v_mul_f32_e32 v1, 0x3fb8aa3b, v1
	v_exp_f32_e32 v39, v1
	v_sub_f32_e32 v1, v41, v154
	v_mul_f32_e32 v1, 0x3d800000, v1
	v_mul_f32_e32 v1, 0x3fb8aa3b, v1
	v_sub_f32_e32 v0, v0, v154
	v_exp_f32_e32 v41, v1
	v_sub_f32_e32 v1, v42, v154
	v_mul_f32_e32 v0, 0x3d800000, v0
	v_mul_f32_e32 v1, 0x3d800000, v1
	v_mul_f32_e32 v0, 0x3fb8aa3b, v0
	v_mul_f32_e32 v1, 0x3fb8aa3b, v1
	v_exp_f32_e32 v128, v0
	v_exp_f32_e32 v40, v1
	v_sub_f32_e32 v1, v43, v154
	v_mul_f32_e32 v1, 0x3d800000, v1
	v_mul_f32_e32 v1, 0x3fb8aa3b, v1
	v_exp_f32_e32 v42, v1
	v_sub_f32_e32 v1, v44, v154
	v_add_f32_e32 v0, 0, v128
	v_mul_f32_e32 v1, 0x3d800000, v1
	v_add_f32_e32 v0, v130, v0
	v_mul_f32_e32 v1, 0x3fb8aa3b, v1
	v_add_f32_e32 v0, v129, v0
	v_exp_f32_e32 v43, v1
	v_sub_f32_e32 v1, v45, v154
	v_add_f32_e32 v0, v131, v0
	v_mul_f32_e32 v1, 0x3d800000, v1
	v_add_f32_e32 v0, v132, v0
	v_mul_f32_e32 v1, 0x3fb8aa3b, v1
	v_add_f32_e32 v0, v133, v0
	v_exp_f32_e32 v160, v1
	v_sub_f32_e32 v1, v46, v154
	v_add_f32_e32 v0, v134, v0
	v_mul_f32_e32 v1, 0x3d800000, v1
	v_add_f32_e32 v0, v135, v0
	v_mul_f32_e32 v1, 0x3fb8aa3b, v1
	v_add_f32_e32 v0, v136, v0
	v_exp_f32_e32 v161, v1
	v_sub_f32_e32 v1, v47, v154
	v_add_f32_e32 v0, v138, v0
	v_mul_f32_e32 v1, 0x3d800000, v1
	v_add_f32_e32 v0, v137, v0
	v_mul_f32_e32 v1, 0x3fb8aa3b, v1
	v_add_f32_e32 v0, v139, v0
	v_exp_f32_e32 v162, v1
	v_sub_f32_e32 v1, v48, v154
	v_add_f32_e32 v0, v140, v0
	v_mul_f32_e32 v1, 0x3d800000, v1
	v_add_f32_e32 v0, v141, v0
	v_mul_f32_e32 v1, 0x3fb8aa3b, v1
	v_add_f32_e32 v0, v142, v0
	v_exp_f32_e32 v163, v1
	v_sub_f32_e32 v1, v49, v154
	v_add_f32_e32 v0, v143, v0
	v_mul_f32_e32 v1, 0x3d800000, v1
	v_add_f32_e32 v0, v144, v0
	v_mul_f32_e32 v1, 0x3fb8aa3b, v1
	v_add_f32_e32 v0, v146, v0
	v_exp_f32_e32 v165, v1
	v_sub_f32_e32 v1, v50, v154
	v_add_f32_e32 v0, v145, v0
	v_mul_f32_e32 v1, 0x3d800000, v1
	v_add_f32_e32 v0, v147, v0
	v_mul_f32_e32 v1, 0x3fb8aa3b, v1
	v_add_f32_e32 v0, v148, v0
	v_exp_f32_e32 v164, v1
	v_sub_f32_e32 v1, v51, v154
	v_add_f32_e32 v0, v149, v0
	v_mul_f32_e32 v1, 0x3d800000, v1
	v_add_f32_e32 v0, v150, v0
	v_mul_f32_e32 v1, 0x3fb8aa3b, v1
	v_add_f32_e32 v0, v151, v0
	v_exp_f32_e32 v166, v1
	v_sub_f32_e32 v1, v52, v154
	v_add_f32_e32 v0, v156, v0
	v_mul_f32_e32 v1, 0x3d800000, v1
	v_add_f32_e32 v0, v158, v0
	v_mul_f32_e32 v1, 0x3fb8aa3b, v1
	v_add_f32_e32 v0, v157, v0
	v_exp_f32_e32 v167, v1
	v_sub_f32_e32 v1, v53, v154
	v_add_f32_e32 v0, v27, v0
	v_mul_f32_e32 v1, 0x3d800000, v1
	v_add_f32_e32 v0, v28, v0
	v_mul_f32_e32 v1, 0x3fb8aa3b, v1
	v_add_f32_e32 v0, v29, v0
	v_exp_f32_e32 v168, v1
	v_sub_f32_e32 v1, v54, v154
	v_add_f32_e32 v0, v30, v0
	v_mul_f32_e32 v1, 0x3d800000, v1
	v_add_f32_e32 v0, v31, v0
	v_mul_f32_e32 v1, 0x3fb8aa3b, v1
	v_add_f32_e32 v0, v32, v0
	v_exp_f32_e32 v169, v1
	v_sub_f32_e32 v1, v55, v154
	v_add_f32_e32 v0, v159, v0
	v_mul_f32_e32 v1, 0x3d800000, v1
	v_add_f32_e32 v0, v33, v0
	v_mul_f32_e32 v1, 0x3fb8aa3b, v1
	v_add_f32_e32 v0, v34, v0
	v_exp_f32_e32 v170, v1
	v_sub_f32_e32 v1, v56, v154
	v_add_f32_e32 v0, v35, v0
	v_mul_f32_e32 v1, 0x3d800000, v1
	v_add_f32_e32 v0, v36, v0
	v_mul_f32_e32 v1, 0x3fb8aa3b, v1
	v_add_f32_e32 v0, v37, v0
	v_exp_f32_e32 v171, v1
	v_sub_f32_e32 v1, v57, v154
	v_add_f32_e32 v0, v38, v0
	v_mul_f32_e32 v1, 0x3d800000, v1
	v_add_f32_e32 v0, v39, v0
	v_mul_f32_e32 v1, 0x3fb8aa3b, v1
	v_add_f32_e32 v0, v41, v0
	v_exp_f32_e32 v172, v1
	v_sub_f32_e32 v1, v58, v154
	v_add_f32_e32 v0, v40, v0
	v_mul_f32_e32 v1, 0x3d800000, v1
	v_add_f32_e32 v0, v42, v0
	v_mul_f32_e32 v1, 0x3fb8aa3b, v1
	v_add_f32_e32 v0, v43, v0
	v_exp_f32_e32 v173, v1
	v_sub_f32_e32 v1, v59, v154
	v_add_f32_e32 v0, v160, v0
	v_mul_f32_e32 v1, 0x3d800000, v1
	v_add_f32_e32 v0, v161, v0
	v_mul_f32_e32 v1, 0x3fb8aa3b, v1
	v_add_f32_e32 v0, v162, v0
	v_exp_f32_e32 v174, v1
	v_sub_f32_e32 v1, v60, v154
	v_add_f32_e32 v0, v163, v0
	v_mul_f32_e32 v1, 0x3d800000, v1
	v_add_f32_e32 v0, v165, v0
	v_mul_f32_e32 v1, 0x3fb8aa3b, v1
	v_add_f32_e32 v0, v164, v0
	v_exp_f32_e32 v175, v1
	v_sub_f32_e32 v1, v61, v154
	v_add_f32_e32 v0, v166, v0
	v_mul_f32_e32 v1, 0x3d800000, v1
	v_add_f32_e32 v0, v167, v0
	v_mul_f32_e32 v1, 0x3fb8aa3b, v1
	v_add_f32_e32 v0, v168, v0
	v_exp_f32_e32 v176, v1
	v_sub_f32_e32 v1, v62, v154
	v_add_f32_e32 v0, v169, v0
	v_mul_f32_e32 v1, 0x3d800000, v1
	v_add_f32_e32 v0, v170, v0
	v_mul_f32_e32 v1, 0x3fb8aa3b, v1
	v_add_f32_e32 v0, v171, v0
	v_exp_f32_e32 v177, v1
	v_sub_f32_e32 v1, v63, v154
	v_add_f32_e32 v0, v172, v0
	v_mul_f32_e32 v1, 0x3d800000, v1
	v_add_f32_e32 v0, v173, v0
	v_mul_f32_e32 v1, 0x3fb8aa3b, v1
	v_add_f32_e32 v0, v174, v0
	v_exp_f32_e32 v178, v1
	v_add_f32_e32 v0, v175, v0
	v_add_f32_e32 v0, v176, v0
	v_add_f32_e32 v0, v177, v0
	v_add_f32_e32 v0, v178, v0
	ds_bpermute_b32 v1, v198, v0
	s_waitcnt lgkmcnt(0)
	v_add_f32_e32 v154, v0, v1
	ds_bpermute_b32 v155, v199, v154
	global_load_dwordx4 v[0:3], v252, s[14:15]
	s_add_u32 s14, s14, 0x10000
	s_addc_u32 s15, s15, 0
	global_load_dwordx4 v[4:7], v252, s[14:15]
	s_add_u32 s14, s14, 0x10000
	s_addc_u32 s15, s15, 0
	global_load_dwordx4 v[8:11], v252, s[14:15]
	s_add_u32 s14, s14, 0x10000
	s_addc_u32 s15, s15, 0
	global_load_dwordx4 v[12:15], v252, s[14:15]
	s_add_u32 s14, s14, 0x10000
	s_addc_u32 s15, s15, 0
	global_load_dwordx4 v[16:19], v252, s[14:15]
	s_add_u32 s14, s14, 0x10000
	s_addc_u32 s15, s15, 0
	global_load_dwordx4 v[20:23], v252, s[14:15]
	s_add_u32 s14, s14, 0x10000
	s_addc_u32 s15, s15, 0
	global_load_dwordx4 v[44:47], v252, s[14:15]
	s_add_u32 s14, s14, 0x10000
	s_addc_u32 s15, s15, 0
	global_load_dwordx4 v[48:51], v252, s[14:15]
	s_add_u32 s14, s14, 0x10000
	s_addc_u32 s15, s15, 0
	global_load_dwordx4 v[52:55], v252, s[14:15]
	s_add_u32 s14, s14, 0x10000
	s_addc_u32 s15, s15, 0
	s_waitcnt vmcnt(15)
	ds_write_b128 v196, v[224:227]
	s_waitcnt vmcnt(14)
	ds_write_b128 v196, v[228:231] offset:8448
	s_waitcnt vmcnt(13)
	ds_write_b128 v196, v[232:235] offset:16896
	s_waitcnt vmcnt(12)
	ds_write_b128 v196, v[236:239] offset:25344
	s_waitcnt vmcnt(11)
	ds_write_b128 v196, v[240:243] offset:33792
	s_waitcnt vmcnt(10)
	ds_write_b128 v196, v[244:247] offset:42240
	s_waitcnt vmcnt(9)
	ds_write_b128 v196, v[248:251] offset:50688
	s_waitcnt vmcnt(8)
	ds_write_b128 v196, v[0:3] offset:59136
	s_waitcnt vmcnt(7)
	ds_write_b128 v253, v[4:7]
	s_waitcnt vmcnt(6)
	ds_write_b128 v253, v[8:11] offset:8448
	s_waitcnt vmcnt(5)
	ds_write_b128 v253, v[12:15] offset:16896
	s_waitcnt vmcnt(4)
	ds_write_b128 v253, v[16:19] offset:25344
	s_waitcnt vmcnt(3)
	ds_write_b128 v253, v[20:23] offset:33792
	s_waitcnt vmcnt(2)
	ds_write_b128 v253, v[44:47] offset:42240
	s_waitcnt vmcnt(1)
	ds_write_b128 v253, v[48:51] offset:50688
	s_waitcnt vmcnt(0)
	ds_write_b128 v253, v[52:55] offset:59136
	s_waitcnt lgkmcnt(0)
	s_barrier
	ds_read2_b64 v[44:47], v211 offset1:4
	ds_read2_b64 v[48:51], v211 offset0:8 offset1:12
	v_cvt_pk_bf16_f32 v16, v64, v65
	v_cvt_pk_bf16_f32 v17, v66, v67
	v_cvt_pk_bf16_f32 v18, v72, v73
	v_cvt_pk_bf16_f32 v19, v74, v75
	v_cvt_pk_bf16_f32 v60, v128, v130
	v_cvt_pk_bf16_f32 v61, v129, v131
	v_cvt_pk_bf16_f32 v62, v132, v133
	v_cvt_pk_bf16_f32 v63, v134, v135
	ds_read2_b64 v[64:67], v211 offset0:16 offset1:20
	s_waitcnt lgkmcnt(2)
	v_mfma_f32_16x16x32_bf16 v[52:55], v[44:47], v[16:19], 0
	v_cvt_pk_bf16_f32 v12, v76, v77
	v_cvt_pk_bf16_f32 v13, v78, v79
	v_cvt_pk_bf16_f32 v14, v80, v81
	v_mfma_f32_16x16x32_bf16 v[44:47], v[44:47], v[60:63], 0
	v_cvt_pk_bf16_f32 v15, v82, v83
	v_cvt_pk_bf16_f32 v56, v136, v138
	v_cvt_pk_bf16_f32 v57, v137, v139
	v_cvt_pk_bf16_f32 v58, v140, v141
	v_cvt_pk_bf16_f32 v59, v142, v143
	ds_read2_b64 v[76:79], v211 offset0:24 offset1:28
	s_waitcnt lgkmcnt(2)
	v_mfma_f32_16x16x32_bf16 v[72:75], v[48:51], v[12:15], v[52:55]
	v_cvt_pk_bf16_f32 v8, v84, v85
	v_cvt_pk_bf16_f32 v9, v86, v87
	v_cvt_pk_bf16_f32 v10, v88, v89
	v_mfma_f32_16x16x32_bf16 v[44:47], v[48:51], v[56:59], v[44:47]
	v_cvt_pk_bf16_f32 v11, v90, v91
	v_cvt_pk_bf16_f32 v52, v144, v146
	v_cvt_pk_bf16_f32 v53, v145, v147
	v_cvt_pk_bf16_f32 v54, v148, v149
	v_cvt_pk_bf16_f32 v55, v150, v151
	s_waitcnt lgkmcnt(1)
	v_mfma_f32_16x16x32_bf16 v[72:75], v[64:67], v[8:11], v[72:75]
	v_cvt_pk_bf16_f32 v4, v92, v93
	v_cvt_pk_bf16_f32 v5, v96, v97
	v_cvt_pk_bf16_f32 v6, v99, v101
	v_mfma_f32_16x16x32_bf16 v[44:47], v[64:67], v[52:55], v[44:47]
	ds_read2_b64 v[64:67], v211 offset0:32 offset1:36
	v_cvt_pk_bf16_f32 v7, v104, v105
	v_cvt_pk_bf16_f32 v48, v156, v158
	v_cvt_pk_bf16_f32 v49, v157, v27
	v_cvt_pk_bf16_f32 v50, v28, v29
	v_cvt_pk_bf16_f32 v51, v30, v31
	s_waitcnt lgkmcnt(1)
	v_mfma_f32_16x16x32_bf16 v[72:75], v[76:79], v[4:7], v[72:75]
	v_cvt_pk_bf16_f32 v0, v107, v109
	v_cvt_pk_bf16_f32 v1, v112, v113
	v_cvt_pk_bf16_f32 v2, v94, v95
	v_mfma_f32_16x16x32_bf16 v[28:31], v[76:79], v[48:51], v[44:47]
	ds_read2_b64 v[76:79], v211 offset0:40 offset1:44
	v_cvt_pk_bf16_f32 v3, v98, v100
	v_cvt_pk_bf16_f32 v20, v102, v103
	v_cvt_pk_bf16_f32 v44, v32, v159
	v_cvt_pk_bf16_f32 v45, v33, v34
	v_cvt_pk_bf16_f32 v46, v35, v36
	v_cvt_pk_bf16_f32 v47, v37, v38
	s_waitcnt lgkmcnt(1)
	v_mfma_f32_16x16x32_bf16 v[72:75], v[64:67], v[0:3], v[72:75]
	v_cvt_pk_bf16_f32 v21, v106, v108
	v_cvt_pk_bf16_f32 v22, v110, v111
	v_cvt_pk_bf16_f32 v23, v114, v116
	v_mfma_f32_16x16x32_bf16 v[30:33], v[64:67], v[44:47], v[28:31]
	ds_read2_b64 v[64:67], v211 offset0:48 offset1:52
	v_cvt_pk_bf16_f32 v36, v39, v41
	v_cvt_pk_bf16_f32 v37, v40, v42
	v_cvt_pk_bf16_f32 v38, v43, v160
	v_cvt_pk_bf16_f32 v39, v161, v162
	s_waitcnt lgkmcnt(1)
	v_mfma_f32_16x16x32_bf16 v[72:75], v[76:79], v[20:23], v[72:75]
	v_cvt_pk_bf16_f32 v24, v115, v118
	v_cvt_pk_bf16_f32 v25, v117, v120
	v_cvt_pk_bf16_f32 v26, v119, v122
	v_mfma_f32_16x16x32_bf16 v[40:43], v[76:79], v[36:39], v[30:33]
	ds_read2_b64 v[76:79], v211 offset0:56 offset1:60
	v_cvt_pk_bf16_f32 v27, v121, v124
	v_cvt_pk_bf16_f32 v28, v123, v126
	v_cvt_pk_bf16_f32 v29, v125, v127
	s_waitcnt lgkmcnt(1)
	v_mfma_f32_16x16x32_bf16 v[72:75], v[64:67], v[24:27], v[72:75]
	v_cvt_pk_bf16_f32 v30, v68, v69
	v_cvt_pk_bf16_f32 v31, v70, v71
	v_add_u32_e32 v84, 0x2000, v211
	v_cvt_pk_bf16_f32 v32, v163, v165
	s_waitcnt lgkmcnt(0)
	v_mfma_f32_16x16x32_bf16 v[68:71], v[76:79], v[28:31], v[72:75]
	v_cvt_pk_bf16_f32 v33, v164, v166
	v_cvt_pk_bf16_f32 v34, v167, v168
	v_cvt_pk_bf16_f32 v35, v169, v170
	ds_read2_b64 v[72:75], v84 offset0:32 offset1:36
	ds_read2_b64 v[80:83], v84 offset0:40 offset1:44
	v_mfma_f32_16x16x32_bf16 v[64:67], v[64:67], v[32:35], v[40:43]
	v_add_u32_e32 v92, 0x4000, v211
	ds_read2_b64 v[88:91], v92 offset0:72 offset1:76
	v_add_u32_e32 v100, v200, v201
	v_cvt_pk_bf16_f32 v40, v171, v172
	v_cvt_pk_bf16_f32 v41, v173, v174
	v_cvt_pk_bf16_f32 v42, v175, v176
	v_cvt_pk_bf16_f32 v43, v177, v178
	ds_read2_b64 v[96:99], v100 offset0:8 offset1:12
	v_add_u32_e32 v108, 0x8000, v211
	v_mfma_f32_16x16x32_bf16 v[64:67], v[76:79], v[40:43], v[64:67]
	ds_read2_b64 v[104:107], v108 offset0:136 offset1:140
	v_add_u32_e32 v116, 0xa000, v211
	ds_read2_b64 v[112:115], v116 offset0:168 offset1:172
	s_waitcnt lgkmcnt(5)
	v_mfma_f32_16x16x32_bf16 v[76:79], v[72:75], v[16:19], 0
	v_add_u32_e32 v124, 0xc000, v211
	ds_read2_b64 v[120:123], v124 offset0:200 offset1:204
	v_add_u32_e32 v132, v200, v202
	v_mfma_f32_16x16x32_bf16 v[72:75], v[72:75], v[60:63], 0
	ds_read2_b64 v[128:131], v132 offset0:8 offset1:12
	v_add_u32_e32 v140, v200, v203
	ds_read2_b64 v[136:139], v140 offset0:8 offset1:12
	s_waitcnt lgkmcnt(7)
	v_mfma_f32_16x16x32_bf16 v[76:79], v[80:83], v[12:15], v[76:79]
	v_add_u32_e32 v148, v200, v204
	ds_read2_b64 v[144:147], v148 offset0:8 offset1:12
	v_add_u32_e32 v160, v200, v205
	v_mfma_f32_16x16x32_bf16 v[72:75], v[80:83], v[56:59], v[72:75]
	ds_read2_b64 v[80:83], v84 offset0:48 offset1:52
	ds_read2_b64 v[156:159], v160 offset0:8 offset1:12
	v_add_u32_e32 v172, v200, v206
	s_waitcnt lgkmcnt(1)
	v_mfma_f32_16x16x32_bf16 v[76:79], v[80:83], v[8:11], v[76:79]
	ds_read2_b64 v[164:167], v172 offset0:8 offset1:12
	s_add_i32 s9, s9, s33
	s_cmpk_gt_i32 s9, 0x1ff
	v_mfma_f32_16x16x32_bf16 v[72:75], v[80:83], v[52:55], v[72:75]
	ds_read2_b64 v[80:83], v84 offset0:56 offset1:60
	s_waitcnt lgkmcnt(0)
	v_mfma_f32_16x16x32_bf16 v[76:79], v[80:83], v[4:7], v[76:79]
	v_mfma_f32_16x16x32_bf16 v[72:75], v[80:83], v[48:51], v[72:75]
	ds_read2_b64 v[80:83], v84 offset0:64 offset1:68
	s_waitcnt lgkmcnt(0)
	v_mfma_f32_16x16x32_bf16 v[76:79], v[80:83], v[0:3], v[76:79]
	v_mfma_f32_16x16x32_bf16 v[72:75], v[80:83], v[44:47], v[72:75]
	ds_read2_b64 v[80:83], v84 offset0:72 offset1:76
	s_waitcnt lgkmcnt(0)
	v_mfma_f32_16x16x32_bf16 v[76:79], v[80:83], v[20:23], v[76:79]
	v_mfma_f32_16x16x32_bf16 v[72:75], v[80:83], v[36:39], v[72:75]
	ds_read2_b64 v[80:83], v84 offset0:80 offset1:84
	s_waitcnt lgkmcnt(0)
	v_mfma_f32_16x16x32_bf16 v[76:79], v[80:83], v[24:27], v[76:79]
	v_mfma_f32_16x16x32_bf16 v[72:75], v[80:83], v[32:35], v[72:75]
	ds_read2_b64 v[80:83], v84 offset0:88 offset1:92
	s_waitcnt lgkmcnt(0)
	v_mfma_f32_16x16x32_bf16 v[76:79], v[80:83], v[28:31], v[76:79]
	v_mfma_f32_16x16x32_bf16 v[72:75], v[80:83], v[40:43], v[72:75]
	ds_read2_b64 v[80:83], v92 offset0:64 offset1:68
	s_waitcnt lgkmcnt(0)
	v_mfma_f32_16x16x32_bf16 v[84:87], v[80:83], v[16:19], 0
	v_mfma_f32_16x16x32_bf16 v[80:83], v[80:83], v[60:63], 0
	v_mfma_f32_16x16x32_bf16 v[84:87], v[88:91], v[12:15], v[84:87]
	v_mfma_f32_16x16x32_bf16 v[80:83], v[88:91], v[56:59], v[80:83]
	ds_read2_b64 v[88:91], v92 offset0:80 offset1:84
	s_waitcnt lgkmcnt(0)
	v_mfma_f32_16x16x32_bf16 v[84:87], v[88:91], v[8:11], v[84:87]
	v_mfma_f32_16x16x32_bf16 v[80:83], v[88:91], v[52:55], v[80:83]
	ds_read2_b64 v[88:91], v92 offset0:88 offset1:92
	s_waitcnt lgkmcnt(0)
	v_mfma_f32_16x16x32_bf16 v[84:87], v[88:91], v[4:7], v[84:87]
	v_mfma_f32_16x16x32_bf16 v[80:83], v[88:91], v[48:51], v[80:83]
	ds_read2_b64 v[88:91], v92 offset0:96 offset1:100
	s_waitcnt lgkmcnt(0)
	v_mfma_f32_16x16x32_bf16 v[84:87], v[88:91], v[0:3], v[84:87]
	v_mfma_f32_16x16x32_bf16 v[80:83], v[88:91], v[44:47], v[80:83]
	ds_read2_b64 v[88:91], v92 offset0:104 offset1:108
	s_waitcnt lgkmcnt(0)
	v_mfma_f32_16x16x32_bf16 v[84:87], v[88:91], v[20:23], v[84:87]
	v_mfma_f32_16x16x32_bf16 v[80:83], v[88:91], v[36:39], v[80:83]
	ds_read2_b64 v[88:91], v92 offset0:112 offset1:116
	s_waitcnt lgkmcnt(0)
	v_mfma_f32_16x16x32_bf16 v[84:87], v[88:91], v[24:27], v[84:87]
	v_mfma_f32_16x16x32_bf16 v[80:83], v[88:91], v[32:35], v[80:83]
	ds_read2_b64 v[88:91], v92 offset0:120 offset1:124
	s_waitcnt lgkmcnt(0)
	v_mfma_f32_16x16x32_bf16 v[84:87], v[88:91], v[28:31], v[84:87]
	v_mfma_f32_16x16x32_bf16 v[80:83], v[88:91], v[40:43], v[80:83]
	ds_read2_b64 v[88:91], v100 offset1:4
	s_waitcnt lgkmcnt(0)
	v_mfma_f32_16x16x32_bf16 v[92:95], v[88:91], v[16:19], 0
	v_mfma_f32_16x16x32_bf16 v[88:91], v[88:91], v[60:63], 0
	v_mfma_f32_16x16x32_bf16 v[92:95], v[96:99], v[12:15], v[92:95]
	v_mfma_f32_16x16x32_bf16 v[88:91], v[96:99], v[56:59], v[88:91]
	ds_read2_b64 v[96:99], v100 offset0:16 offset1:20
	s_waitcnt lgkmcnt(0)
	v_mfma_f32_16x16x32_bf16 v[92:95], v[96:99], v[8:11], v[92:95]
	v_mfma_f32_16x16x32_bf16 v[88:91], v[96:99], v[52:55], v[88:91]
	ds_read2_b64 v[96:99], v100 offset0:24 offset1:28
	s_waitcnt lgkmcnt(0)
	v_mfma_f32_16x16x32_bf16 v[92:95], v[96:99], v[4:7], v[92:95]
	v_mfma_f32_16x16x32_bf16 v[88:91], v[96:99], v[48:51], v[88:91]
	ds_read2_b64 v[96:99], v100 offset0:32 offset1:36
	s_waitcnt lgkmcnt(0)
	v_mfma_f32_16x16x32_bf16 v[92:95], v[96:99], v[0:3], v[92:95]
	v_mfma_f32_16x16x32_bf16 v[88:91], v[96:99], v[44:47], v[88:91]
	ds_read2_b64 v[96:99], v100 offset0:40 offset1:44
	s_waitcnt lgkmcnt(0)
	v_mfma_f32_16x16x32_bf16 v[92:95], v[96:99], v[20:23], v[92:95]
	v_mfma_f32_16x16x32_bf16 v[88:91], v[96:99], v[36:39], v[88:91]
	ds_read2_b64 v[96:99], v100 offset0:48 offset1:52
	s_waitcnt lgkmcnt(0)
	v_mfma_f32_16x16x32_bf16 v[92:95], v[96:99], v[24:27], v[92:95]
	v_mfma_f32_16x16x32_bf16 v[88:91], v[96:99], v[32:35], v[88:91]
	ds_read2_b64 v[96:99], v100 offset0:56 offset1:60
	s_waitcnt lgkmcnt(0)
	v_mfma_f32_16x16x32_bf16 v[92:95], v[96:99], v[28:31], v[92:95]
	v_mfma_f32_16x16x32_bf16 v[88:91], v[96:99], v[40:43], v[88:91]
	ds_read2_b64 v[96:99], v108 offset0:128 offset1:132
	s_waitcnt lgkmcnt(0)
	v_mfma_f32_16x16x32_bf16 v[100:103], v[96:99], v[16:19], 0
	v_mfma_f32_16x16x32_bf16 v[96:99], v[96:99], v[60:63], 0
	v_mfma_f32_16x16x32_bf16 v[100:103], v[104:107], v[12:15], v[100:103]
	v_mfma_f32_16x16x32_bf16 v[96:99], v[104:107], v[56:59], v[96:99]
	ds_read2_b64 v[104:107], v108 offset0:144 offset1:148
	s_waitcnt lgkmcnt(0)
	v_mfma_f32_16x16x32_bf16 v[100:103], v[104:107], v[8:11], v[100:103]
	v_mfma_f32_16x16x32_bf16 v[96:99], v[104:107], v[52:55], v[96:99]
	ds_read2_b64 v[104:107], v108 offset0:152 offset1:156
	s_waitcnt lgkmcnt(0)
	v_mfma_f32_16x16x32_bf16 v[100:103], v[104:107], v[4:7], v[100:103]
	v_mfma_f32_16x16x32_bf16 v[96:99], v[104:107], v[48:51], v[96:99]
	ds_read2_b64 v[104:107], v108 offset0:160 offset1:164
	s_waitcnt lgkmcnt(0)
	v_mfma_f32_16x16x32_bf16 v[100:103], v[104:107], v[0:3], v[100:103]
	v_mfma_f32_16x16x32_bf16 v[96:99], v[104:107], v[44:47], v[96:99]
	ds_read2_b64 v[104:107], v108 offset0:168 offset1:172
	s_waitcnt lgkmcnt(0)
	v_mfma_f32_16x16x32_bf16 v[100:103], v[104:107], v[20:23], v[100:103]
	v_mfma_f32_16x16x32_bf16 v[96:99], v[104:107], v[36:39], v[96:99]
	ds_read2_b64 v[104:107], v108 offset0:176 offset1:180
	s_waitcnt lgkmcnt(0)
	v_mfma_f32_16x16x32_bf16 v[100:103], v[104:107], v[24:27], v[100:103]
	v_mfma_f32_16x16x32_bf16 v[96:99], v[104:107], v[32:35], v[96:99]
	ds_read2_b64 v[104:107], v108 offset0:184 offset1:188
	s_waitcnt lgkmcnt(0)
	v_mfma_f32_16x16x32_bf16 v[100:103], v[104:107], v[28:31], v[100:103]
	v_mfma_f32_16x16x32_bf16 v[96:99], v[104:107], v[40:43], v[96:99]
	ds_read2_b64 v[104:107], v116 offset0:160 offset1:164
	s_waitcnt lgkmcnt(0)
	v_mfma_f32_16x16x32_bf16 v[108:111], v[104:107], v[16:19], 0
	v_mfma_f32_16x16x32_bf16 v[104:107], v[104:107], v[60:63], 0
	v_mfma_f32_16x16x32_bf16 v[108:111], v[112:115], v[12:15], v[108:111]
	v_mfma_f32_16x16x32_bf16 v[104:107], v[112:115], v[56:59], v[104:107]
	ds_read2_b64 v[112:115], v116 offset0:176 offset1:180
	s_waitcnt lgkmcnt(0)
	v_mfma_f32_16x16x32_bf16 v[108:111], v[112:115], v[8:11], v[108:111]
	v_mfma_f32_16x16x32_bf16 v[104:107], v[112:115], v[52:55], v[104:107]
	ds_read2_b64 v[112:115], v116 offset0:184 offset1:188
	s_waitcnt lgkmcnt(0)
	v_mfma_f32_16x16x32_bf16 v[108:111], v[112:115], v[4:7], v[108:111]
	v_mfma_f32_16x16x32_bf16 v[104:107], v[112:115], v[48:51], v[104:107]
	ds_read2_b64 v[112:115], v116 offset0:192 offset1:196
	s_waitcnt lgkmcnt(0)
	v_mfma_f32_16x16x32_bf16 v[108:111], v[112:115], v[0:3], v[108:111]
	v_mfma_f32_16x16x32_bf16 v[104:107], v[112:115], v[44:47], v[104:107]
	ds_read2_b64 v[112:115], v116 offset0:200 offset1:204
	s_waitcnt lgkmcnt(0)
	v_mfma_f32_16x16x32_bf16 v[108:111], v[112:115], v[20:23], v[108:111]
	v_mfma_f32_16x16x32_bf16 v[104:107], v[112:115], v[36:39], v[104:107]
	ds_read2_b64 v[112:115], v116 offset0:208 offset1:212
	s_waitcnt lgkmcnt(0)
	v_mfma_f32_16x16x32_bf16 v[108:111], v[112:115], v[24:27], v[108:111]
	v_mfma_f32_16x16x32_bf16 v[104:107], v[112:115], v[32:35], v[104:107]
	ds_read2_b64 v[112:115], v116 offset0:216 offset1:220
	s_waitcnt lgkmcnt(0)
	v_mfma_f32_16x16x32_bf16 v[108:111], v[112:115], v[28:31], v[108:111]
	v_mfma_f32_16x16x32_bf16 v[104:107], v[112:115], v[40:43], v[104:107]
	ds_read2_b64 v[112:115], v124 offset0:192 offset1:196
	s_waitcnt lgkmcnt(0)
	v_mfma_f32_16x16x32_bf16 v[116:119], v[112:115], v[16:19], 0
	v_mfma_f32_16x16x32_bf16 v[112:115], v[112:115], v[60:63], 0
	v_mfma_f32_16x16x32_bf16 v[116:119], v[120:123], v[12:15], v[116:119]
	v_mfma_f32_16x16x32_bf16 v[112:115], v[120:123], v[56:59], v[112:115]
	ds_read2_b64 v[120:123], v124 offset0:208 offset1:212
	s_waitcnt lgkmcnt(0)
	v_mfma_f32_16x16x32_bf16 v[116:119], v[120:123], v[8:11], v[116:119]
	v_mfma_f32_16x16x32_bf16 v[112:115], v[120:123], v[52:55], v[112:115]
	ds_read2_b64 v[120:123], v124 offset0:216 offset1:220
	s_waitcnt lgkmcnt(0)
	v_mfma_f32_16x16x32_bf16 v[116:119], v[120:123], v[4:7], v[116:119]
	v_mfma_f32_16x16x32_bf16 v[112:115], v[120:123], v[48:51], v[112:115]
	ds_read2_b64 v[120:123], v124 offset0:224 offset1:228
	s_waitcnt lgkmcnt(0)
	v_mfma_f32_16x16x32_bf16 v[116:119], v[120:123], v[0:3], v[116:119]
	v_mfma_f32_16x16x32_bf16 v[112:115], v[120:123], v[44:47], v[112:115]
	ds_read2_b64 v[120:123], v124 offset0:232 offset1:236
	s_waitcnt lgkmcnt(0)
	v_mfma_f32_16x16x32_bf16 v[116:119], v[120:123], v[20:23], v[116:119]
	v_mfma_f32_16x16x32_bf16 v[112:115], v[120:123], v[36:39], v[112:115]
	ds_read2_b64 v[120:123], v124 offset0:240 offset1:244
	s_waitcnt lgkmcnt(0)
	v_mfma_f32_16x16x32_bf16 v[116:119], v[120:123], v[24:27], v[116:119]
	v_mfma_f32_16x16x32_bf16 v[112:115], v[120:123], v[32:35], v[112:115]
	ds_read2_b64 v[120:123], v124 offset0:248 offset1:252
	s_waitcnt lgkmcnt(0)
	v_mfma_f32_16x16x32_bf16 v[116:119], v[120:123], v[28:31], v[116:119]
	v_mfma_f32_16x16x32_bf16 v[112:115], v[120:123], v[40:43], v[112:115]
	ds_read2_b64 v[120:123], v132 offset1:4
	s_waitcnt lgkmcnt(0)
	v_mfma_f32_16x16x32_bf16 v[124:127], v[120:123], v[16:19], 0
	v_mfma_f32_16x16x32_bf16 v[120:123], v[120:123], v[60:63], 0
	v_mfma_f32_16x16x32_bf16 v[124:127], v[128:131], v[12:15], v[124:127]
	v_mfma_f32_16x16x32_bf16 v[120:123], v[128:131], v[56:59], v[120:123]
	ds_read2_b64 v[128:131], v132 offset0:16 offset1:20
	s_waitcnt lgkmcnt(0)
	v_mfma_f32_16x16x32_bf16 v[124:127], v[128:131], v[8:11], v[124:127]
	v_mfma_f32_16x16x32_bf16 v[120:123], v[128:131], v[52:55], v[120:123]
	ds_read2_b64 v[128:131], v132 offset0:24 offset1:28
	s_waitcnt lgkmcnt(0)
	v_mfma_f32_16x16x32_bf16 v[124:127], v[128:131], v[4:7], v[124:127]
	v_mfma_f32_16x16x32_bf16 v[120:123], v[128:131], v[48:51], v[120:123]
	ds_read2_b64 v[128:131], v132 offset0:32 offset1:36
	s_waitcnt lgkmcnt(0)
	v_mfma_f32_16x16x32_bf16 v[124:127], v[128:131], v[0:3], v[124:127]
	v_mfma_f32_16x16x32_bf16 v[120:123], v[128:131], v[44:47], v[120:123]
	ds_read2_b64 v[128:131], v132 offset0:40 offset1:44
	s_waitcnt lgkmcnt(0)
	v_mfma_f32_16x16x32_bf16 v[124:127], v[128:131], v[20:23], v[124:127]
	v_mfma_f32_16x16x32_bf16 v[120:123], v[128:131], v[36:39], v[120:123]
	ds_read2_b64 v[128:131], v132 offset0:48 offset1:52
	s_waitcnt lgkmcnt(0)
	v_mfma_f32_16x16x32_bf16 v[124:127], v[128:131], v[24:27], v[124:127]
	v_mfma_f32_16x16x32_bf16 v[120:123], v[128:131], v[32:35], v[120:123]
	ds_read2_b64 v[128:131], v132 offset0:56 offset1:60
	s_waitcnt lgkmcnt(0)
	v_mfma_f32_16x16x32_bf16 v[124:127], v[128:131], v[28:31], v[124:127]
	v_mfma_f32_16x16x32_bf16 v[120:123], v[128:131], v[40:43], v[120:123]
	ds_read2_b64 v[128:131], v140 offset1:4
	s_waitcnt lgkmcnt(0)
	v_mfma_f32_16x16x32_bf16 v[132:135], v[128:131], v[16:19], 0
	v_mfma_f32_16x16x32_bf16 v[128:131], v[128:131], v[60:63], 0
	v_mfma_f32_16x16x32_bf16 v[132:135], v[136:139], v[12:15], v[132:135]
	v_mfma_f32_16x16x32_bf16 v[128:131], v[136:139], v[56:59], v[128:131]
	ds_read2_b64 v[136:139], v140 offset0:16 offset1:20
	s_waitcnt lgkmcnt(0)
	v_mfma_f32_16x16x32_bf16 v[132:135], v[136:139], v[8:11], v[132:135]
	v_mfma_f32_16x16x32_bf16 v[128:131], v[136:139], v[52:55], v[128:131]
	ds_read2_b64 v[136:139], v140 offset0:24 offset1:28
	s_waitcnt lgkmcnt(0)
	v_mfma_f32_16x16x32_bf16 v[132:135], v[136:139], v[4:7], v[132:135]
	v_mfma_f32_16x16x32_bf16 v[128:131], v[136:139], v[48:51], v[128:131]
	ds_read2_b64 v[136:139], v140 offset0:32 offset1:36
	s_waitcnt lgkmcnt(0)
	v_mfma_f32_16x16x32_bf16 v[132:135], v[136:139], v[0:3], v[132:135]
	v_mfma_f32_16x16x32_bf16 v[128:131], v[136:139], v[44:47], v[128:131]
	ds_read2_b64 v[136:139], v140 offset0:40 offset1:44
	s_waitcnt lgkmcnt(0)
	v_mfma_f32_16x16x32_bf16 v[132:135], v[136:139], v[20:23], v[132:135]
	v_mfma_f32_16x16x32_bf16 v[128:131], v[136:139], v[36:39], v[128:131]
	ds_read2_b64 v[136:139], v140 offset0:48 offset1:52
	s_waitcnt lgkmcnt(0)
	v_mfma_f32_16x16x32_bf16 v[132:135], v[136:139], v[24:27], v[132:135]
	v_mfma_f32_16x16x32_bf16 v[128:131], v[136:139], v[32:35], v[128:131]
	ds_read2_b64 v[136:139], v140 offset0:56 offset1:60
	s_waitcnt lgkmcnt(0)
	v_mfma_f32_16x16x32_bf16 v[132:135], v[136:139], v[28:31], v[132:135]
	v_mfma_f32_16x16x32_bf16 v[128:131], v[136:139], v[40:43], v[128:131]
	ds_read2_b64 v[136:139], v148 offset1:4
	s_waitcnt lgkmcnt(0)
	v_mfma_f32_16x16x32_bf16 v[140:143], v[136:139], v[16:19], 0
	v_mfma_f32_16x16x32_bf16 v[136:139], v[136:139], v[60:63], 0
	v_mfma_f32_16x16x32_bf16 v[140:143], v[144:147], v[12:15], v[140:143]
	v_mfma_f32_16x16x32_bf16 v[136:139], v[144:147], v[56:59], v[136:139]
	ds_read2_b64 v[144:147], v148 offset0:16 offset1:20
	s_waitcnt lgkmcnt(0)
	v_mfma_f32_16x16x32_bf16 v[140:143], v[144:147], v[8:11], v[140:143]
	v_mfma_f32_16x16x32_bf16 v[136:139], v[144:147], v[52:55], v[136:139]
	ds_read2_b64 v[144:147], v148 offset0:24 offset1:28
	s_waitcnt lgkmcnt(0)
	v_mfma_f32_16x16x32_bf16 v[140:143], v[144:147], v[4:7], v[140:143]
	v_mfma_f32_16x16x32_bf16 v[136:139], v[144:147], v[48:51], v[136:139]
	ds_read2_b64 v[144:147], v148 offset0:32 offset1:36
	s_waitcnt lgkmcnt(0)
	v_mfma_f32_16x16x32_bf16 v[140:143], v[144:147], v[0:3], v[140:143]
	v_mfma_f32_16x16x32_bf16 v[136:139], v[144:147], v[44:47], v[136:139]
	ds_read2_b64 v[144:147], v148 offset0:40 offset1:44
	s_waitcnt lgkmcnt(0)
	v_mfma_f32_16x16x32_bf16 v[140:143], v[144:147], v[20:23], v[140:143]
	v_mfma_f32_16x16x32_bf16 v[136:139], v[144:147], v[36:39], v[136:139]
	ds_read2_b64 v[144:147], v148 offset0:48 offset1:52
	s_waitcnt lgkmcnt(0)
	v_mfma_f32_16x16x32_bf16 v[140:143], v[144:147], v[24:27], v[140:143]
	v_mfma_f32_16x16x32_bf16 v[136:139], v[144:147], v[32:35], v[136:139]
	ds_read2_b64 v[144:147], v148 offset0:56 offset1:60
	s_waitcnt lgkmcnt(0)
	v_mfma_f32_16x16x32_bf16 v[140:143], v[144:147], v[28:31], v[140:143]
	v_mfma_f32_16x16x32_bf16 v[136:139], v[144:147], v[40:43], v[136:139]
	ds_read2_b64 v[144:147], v160 offset1:4
	s_waitcnt lgkmcnt(0)
	v_mfma_f32_16x16x32_bf16 v[148:151], v[144:147], v[16:19], 0
	v_mfma_f32_16x16x32_bf16 v[144:147], v[144:147], v[60:63], 0
	v_mfma_f32_16x16x32_bf16 v[148:151], v[156:159], v[12:15], v[148:151]
	v_mfma_f32_16x16x32_bf16 v[144:147], v[156:159], v[56:59], v[144:147]
	ds_read2_b64 v[156:159], v160 offset0:16 offset1:20
	s_waitcnt lgkmcnt(0)
	v_mfma_f32_16x16x32_bf16 v[148:151], v[156:159], v[8:11], v[148:151]
	v_mfma_f32_16x16x32_bf16 v[144:147], v[156:159], v[52:55], v[144:147]
	ds_read2_b64 v[156:159], v160 offset0:24 offset1:28
	s_waitcnt lgkmcnt(0)
	v_mfma_f32_16x16x32_bf16 v[148:151], v[156:159], v[4:7], v[148:151]
	v_mfma_f32_16x16x32_bf16 v[144:147], v[156:159], v[48:51], v[144:147]
	ds_read2_b64 v[156:159], v160 offset0:32 offset1:36
	s_waitcnt lgkmcnt(0)
	v_mfma_f32_16x16x32_bf16 v[148:151], v[156:159], v[0:3], v[148:151]
	v_mfma_f32_16x16x32_bf16 v[144:147], v[156:159], v[44:47], v[144:147]
	ds_read2_b64 v[156:159], v160 offset0:40 offset1:44
	s_waitcnt lgkmcnt(0)
	v_mfma_f32_16x16x32_bf16 v[148:151], v[156:159], v[20:23], v[148:151]
	v_mfma_f32_16x16x32_bf16 v[144:147], v[156:159], v[36:39], v[144:147]
	ds_read2_b64 v[156:159], v160 offset0:48 offset1:52
	s_waitcnt lgkmcnt(0)
	v_mfma_f32_16x16x32_bf16 v[148:151], v[156:159], v[24:27], v[148:151]
	v_mfma_f32_16x16x32_bf16 v[144:147], v[156:159], v[32:35], v[144:147]
	ds_read2_b64 v[156:159], v160 offset0:56 offset1:60
	s_waitcnt lgkmcnt(0)
	v_mfma_f32_16x16x32_bf16 v[148:151], v[156:159], v[28:31], v[148:151]
	v_mfma_f32_16x16x32_bf16 v[144:147], v[156:159], v[40:43], v[144:147]
	ds_read2_b64 v[156:159], v172 offset1:4
	s_waitcnt lgkmcnt(0)
	v_mfma_f32_16x16x32_bf16 v[160:163], v[156:159], v[16:19], 0
	v_mfma_f32_16x16x32_bf16 v[156:159], v[156:159], v[60:63], 0
	v_mfma_f32_16x16x32_bf16 v[160:163], v[164:167], v[12:15], v[160:163]
	v_mfma_f32_16x16x32_bf16 v[156:159], v[164:167], v[56:59], v[156:159]
	ds_read2_b64 v[164:167], v172 offset0:16 offset1:20
	s_waitcnt lgkmcnt(0)
	v_mfma_f32_16x16x32_bf16 v[160:163], v[164:167], v[8:11], v[160:163]
	v_mfma_f32_16x16x32_bf16 v[156:159], v[164:167], v[52:55], v[156:159]
	ds_read2_b64 v[164:167], v172 offset0:24 offset1:28
	s_waitcnt lgkmcnt(0)
	v_mfma_f32_16x16x32_bf16 v[160:163], v[164:167], v[4:7], v[160:163]
	v_mfma_f32_16x16x32_bf16 v[156:159], v[164:167], v[48:51], v[156:159]
	ds_read2_b64 v[164:167], v172 offset0:32 offset1:36
	s_waitcnt lgkmcnt(0)
	v_mfma_f32_16x16x32_bf16 v[160:163], v[164:167], v[0:3], v[160:163]
	v_mfma_f32_16x16x32_bf16 v[156:159], v[164:167], v[44:47], v[156:159]
	ds_read2_b64 v[164:167], v172 offset0:40 offset1:44
	s_waitcnt lgkmcnt(0)
	v_mfma_f32_16x16x32_bf16 v[160:163], v[164:167], v[20:23], v[160:163]
	v_mfma_f32_16x16x32_bf16 v[156:159], v[164:167], v[36:39], v[156:159]
	ds_read2_b64 v[164:167], v172 offset0:48 offset1:52
	ds_read2_b64 v[172:175], v172 offset0:56 offset1:60
	s_waitcnt lgkmcnt(1)
	v_mfma_f32_16x16x32_bf16 v[168:171], v[164:167], v[24:27], v[160:163]
	s_nop 2
	v_add_u32_e32 v163, v200, v207
	ds_read2_b64 v[176:179], v163 offset1:4
	v_add_f32_e32 v160, v152, v153
	v_add_f32_e32 v161, v154, v155
	v_mfma_f32_16x16x32_bf16 v[152:155], v[164:167], v[32:35], v[156:159]
	v_rcp_f32_e32 v160, v160
	v_rcp_f32_e32 v162, v161
	v_lshl_add_u64 v[164:165], v[194:195], 1, s[62:63]
	s_waitcnt lgkmcnt(1)
	v_mfma_f32_16x16x32_bf16 v[156:159], v[172:175], v[28:31], v[168:171]
	v_lshl_add_u64 v[164:165], v[164:165], 0, s[0:1]
	v_pk_mul_f32 v[68:69], v[160:161], v[68:69] op_sel_hi:[0,1]
	v_pk_mul_f32 v[70:71], v[160:161], v[70:71] op_sel_hi:[0,1]
	ds_read2_b64 v[166:169], v163 offset0:8 offset1:12
	v_mfma_f32_16x16x32_bf16 v[152:155], v[172:175], v[40:43], v[152:155]
	v_lshl_add_u64 v[164:165], v[164:165], 0, v[188:189]
	v_cvt_pk_bf16_f32 v174, v68, v69
	v_cvt_pk_bf16_f32 v175, v70, v71
	s_waitcnt lgkmcnt(1)
	v_mfma_f32_16x16x32_bf16 v[170:173], v[176:179], v[16:19], 0
	v_mov_b32_e32 v216, v174
	v_mov_b32_e32 v217, v175
	v_pk_mul_f32 v[174:175], v[162:163], v[64:65] op_sel_hi:[0,1]
	v_pk_mul_f32 v[76:77], v[160:161], v[76:77] op_sel_hi:[0,1]
	v_mfma_f32_16x16x32_bf16 v[68:71], v[176:179], v[60:63], 0
	v_mul_f32_e64 v176, v162, v66
	v_mul_f32_e64 v177, v162, v67
	v_cvt_pk_bf16_f32 v178, v174, v175
	v_cvt_pk_bf16_f32 v179, v176, v177
	s_waitcnt lgkmcnt(0)
	v_mfma_f32_16x16x32_bf16 v[64:67], v[166:169], v[12:15], v[170:173]
	ds_read2_b64 v[174:177], v163 offset0:24 offset1:28
	v_pk_mul_f32 v[78:79], v[160:161], v[78:79] op_sel_hi:[0,1]
	v_pk_mul_f32 v[72:73], v[162:163], v[72:73] op_sel_hi:[0,1]
	ds_read2_b64 v[170:173], v163 offset0:16 offset1:20
	v_mfma_f32_16x16x32_bf16 v[68:71], v[166:169], v[56:59], v[68:71]
	v_cvt_pk_bf16_f32 v168, v76, v77
	v_cvt_pk_bf16_f32 v169, v78, v79
	ds_read2_b64 v[76:79], v163 offset0:32 offset1:36
	s_waitcnt lgkmcnt(1)
	v_mfma_f32_16x16x32_bf16 v[64:67], v[170:173], v[8:11], v[64:67]
	v_mul_f32_e64 v74, v162, v74
	v_mul_f32_e64 v75, v162, v75
	v_mov_b32_e32 v218, v168
	v_mov_b32_e32 v219, v169
	v_mbcnt_lo_u32_b32 v236, -1, 0
	v_mbcnt_hi_u32_b32 v236, -1, v236
	v_and_b32_e32 v236, 16, v236
	v_mul_u32_u24_e32 v236, 3, v236
	v_lshrrev_b32_e32 v236, 1, v236
	v_mov_b32_e32 v237, 0
	s_nop 0
	v_lshl_add_u64 v[232:233], v[164:165], 0, v[236:237]
	s_nop 1
	v_permlane16_swap_b32 v216, v218
	v_permlane16_swap_b32 v217, v219
	global_store_dwordx4 v[232:233], v[216:219], off
	v_cvt_pk_bf16_f32 v168, v72, v73
	v_mfma_f32_16x16x32_bf16 v[68:71], v[170:173], v[52:55], v[68:71]
	v_cvt_pk_bf16_f32 v169, v74, v75
	ds_read2_b64 v[72:75], v163 offset0:40 offset1:44
	v_add_co_u32_e32 v166, vcc, s8, v164
	v_mfma_f32_16x16x32_bf16 v[64:67], v[174:177], v[4:7], v[64:67]
	v_mul_f32_e64 v80, v162, v80
	v_mul_f32_e64 v81, v162, v81
	v_pk_mul_f32 v[82:83], v[162:163], v[82:83] op_sel_hi:[0,1]
	v_addc_co_u32_e32 v167, vcc, 0, v165, vcc
	v_mfma_f32_16x16x32_bf16 v[68:71], v[174:177], v[48:51], v[68:71]
	v_cvt_pk_bf16_f32 v80, v80, v81
	v_cvt_pk_bf16_f32 v81, v82, v83
	v_pk_mul_f32 v[84:85], v[160:161], v[84:85] op_sel_hi:[0,1]
	s_waitcnt lgkmcnt(1)
	v_mfma_f32_16x16x32_bf16 v[64:67], v[76:79], v[0:3], v[64:67]
	v_mul_f32_e64 v86, v160, v86
	v_mul_f32_e64 v87, v160, v87
	v_mov_b32_e32 v220, v80
	v_mov_b32_e32 v221, v81
	v_pk_mul_f32 v[80:81], v[160:161], v[92:93] op_sel_hi:[0,1]
	v_mfma_f32_16x16x32_bf16 v[68:71], v[76:79], v[44:47], v[68:71]
	ds_read2_b64 v[76:79], v163 offset0:48 offset1:52
	v_add_u32_e32 v92, v200, v208
	v_cvt_pk_bf16_f32 v84, v84, v85
	s_waitcnt lgkmcnt(1)
	v_mfma_f32_16x16x32_bf16 v[64:67], v[72:75], v[20:23], v[64:67]
	v_cvt_pk_bf16_f32 v85, v86, v87
	v_cvt_pk_bf16_f32 v86, v80, v81
	ds_read2_b64 v[80:83], v92 offset1:4
	v_mfma_f32_16x16x32_bf16 v[68:71], v[72:75], v[36:39], v[68:71]
	ds_read2_b64 v[72:75], v163 offset0:56 offset1:60
	v_mov_b32_e32 v224, v84
	v_mov_b32_e32 v225, v85
	v_pk_mul_f32 v[84:85], v[160:161], v[94:95] op_sel_hi:[0,1]
	s_waitcnt lgkmcnt(2)
	v_mfma_f32_16x16x32_bf16 v[64:67], v[76:79], v[24:27], v[64:67]
	v_cvt_pk_bf16_f32 v87, v84, v85
	v_mov_b32_e32 v226, v86
	v_mov_b32_e32 v227, v87
	s_nop 1
	v_permlane16_swap_b32 v224, v226
	v_permlane16_swap_b32 v225, v227
	global_store_dwordx4 v[232:233], v[224:227], off offset:64
	v_pk_mul_f32 v[84:85], v[162:163], v[88:89] op_sel_hi:[0,1]
	v_mfma_f32_16x16x32_bf16 v[76:79], v[76:79], v[32:35], v[68:71]
	v_mul_f32_e64 v86, v162, v90
	v_mul_f32_e64 v87, v162, v91
	v_cvt_pk_bf16_f32 v84, v84, v85
	v_cvt_pk_bf16_f32 v85, v86, v87
	s_waitcnt lgkmcnt(0)
	v_mfma_f32_16x16x32_bf16 v[68:71], v[72:75], v[28:31], v[64:67]
	v_mov_b32_e32 v222, v84
	v_mov_b32_e32 v223, v85
	s_nop 0
	v_lshl_add_u64 v[234:235], v[166:167], 0, v[236:237]
	s_nop 1
	v_permlane16_swap_b32 v220, v222
	v_permlane16_swap_b32 v221, v223
	global_store_dwordx4 v[234:235], v[220:223], off offset:64
	v_pk_mul_f32 v[84:85], v[160:161], v[100:101] op_sel_hi:[0,1]
	v_cvt_pk_bf16_f32 v90, v84, v85
	v_mfma_f32_16x16x32_bf16 v[64:67], v[72:75], v[40:43], v[76:79]
	ds_read2_b64 v[72:75], v92 offset0:8 offset1:12
	ds_read2_b64 v[84:87], v92 offset0:16 offset1:20
	v_pk_mul_f32 v[88:89], v[160:161], v[102:103] op_sel_hi:[0,1]
	v_mfma_f32_16x16x32_bf16 v[76:79], v[80:83], v[16:19], 0
	v_cvt_pk_bf16_f32 v91, v88, v89
	v_mov_b32_e32 v228, v90
	v_mov_b32_e32 v229, v91
	v_pk_mul_f32 v[88:89], v[162:163], v[96:97] op_sel_hi:[0,1]
	v_mfma_f32_16x16x32_bf16 v[80:83], v[80:83], v[60:63], 0
	v_mul_f32_e64 v90, v162, v98
	v_mul_f32_e64 v91, v162, v99
	v_cvt_pk_bf16_f32 v88, v88, v89
	v_cvt_pk_bf16_f32 v89, v90, v91
	s_waitcnt lgkmcnt(1)
	v_mfma_f32_16x16x32_bf16 v[76:79], v[72:75], v[12:15], v[76:79]
	v_mov_b32_e32 v216, v88
	v_mov_b32_e32 v217, v89
	v_pk_mul_f32 v[88:89], v[160:161], v[108:109] op_sel_hi:[0,1]
	v_pk_mul_f32 v[90:91], v[160:161], v[110:111] op_sel_hi:[0,1]
	v_mfma_f32_16x16x32_bf16 v[72:75], v[72:75], v[56:59], v[80:83]
	v_add_u32_e32 v100, v200, v209
	v_cvt_pk_bf16_f32 v88, v88, v89
	v_cvt_pk_bf16_f32 v89, v90, v91
	ds_read2_b64 v[80:83], v92 offset0:24 offset1:28
	s_waitcnt lgkmcnt(1)
	v_mfma_f32_16x16x32_bf16 v[76:79], v[84:87], v[8:11], v[76:79]
	v_mov_b32_e32 v230, v88
	v_mov_b32_e32 v231, v89
	s_nop 1
	v_permlane16_swap_b32 v228, v230
	v_permlane16_swap_b32 v229, v231
	global_store_dwordx4 v[232:233], v[228:231], off offset:128
	v_pk_mul_f32 v[88:89], v[162:163], v[104:105] op_sel_hi:[0,1]
	v_pk_mul_f32 v[90:91], v[162:163], v[106:107] op_sel_hi:[0,1]
	v_mfma_f32_16x16x32_bf16 v[72:75], v[84:87], v[52:55], v[72:75]
	ds_read2_b64 v[84:87], v92 offset0:32 offset1:36
	v_cvt_pk_bf16_f32 v88, v88, v89
	v_cvt_pk_bf16_f32 v89, v90, v91
	s_waitcnt lgkmcnt(1)
	v_mfma_f32_16x16x32_bf16 v[76:79], v[80:83], v[4:7], v[76:79]
	v_mov_b32_e32 v218, v88
	v_mov_b32_e32 v219, v89
	s_nop 1
	v_permlane16_swap_b32 v216, v218
	v_permlane16_swap_b32 v217, v219
	global_store_dwordx4 v[234:235], v[216:219], off offset:128
	v_pk_mul_f32 v[88:89], v[160:161], v[116:117] op_sel_hi:[0,1]
	v_pk_mul_f32 v[90:91], v[160:161], v[118:119] op_sel_hi:[0,1]
	v_mfma_f32_16x16x32_bf16 v[72:75], v[80:83], v[48:51], v[72:75]
	ds_read2_b64 v[80:83], v92 offset0:40 offset1:44
	v_cvt_pk_bf16_f32 v88, v88, v89
	v_cvt_pk_bf16_f32 v89, v90, v91
	s_waitcnt lgkmcnt(1)
	v_mfma_f32_16x16x32_bf16 v[76:79], v[84:87], v[0:3], v[76:79]
	v_mov_b32_e32 v224, v88
	v_mov_b32_e32 v225, v89
	v_pk_mul_f32 v[88:89], v[162:163], v[112:113] op_sel_hi:[0,1]
	v_pk_mul_f32 v[90:91], v[162:163], v[114:115] op_sel_hi:[0,1]
	v_mfma_f32_16x16x32_bf16 v[72:75], v[84:87], v[44:47], v[72:75]
	ds_read2_b64 v[84:87], v92 offset0:48 offset1:52
	v_cvt_pk_bf16_f32 v88, v88, v89
	v_cvt_pk_bf16_f32 v89, v90, v91
	s_waitcnt lgkmcnt(1)
	v_mfma_f32_16x16x32_bf16 v[76:79], v[80:83], v[20:23], v[76:79]
	v_mov_b32_e32 v220, v88
	v_mov_b32_e32 v221, v89
	v_pk_mul_f32 v[88:89], v[160:161], v[124:125] op_sel_hi:[0,1]
	v_pk_mul_f32 v[90:91], v[160:161], v[126:127] op_sel_hi:[0,1]
	v_mfma_f32_16x16x32_bf16 v[72:75], v[80:83], v[36:39], v[72:75]
	ds_read2_b64 v[80:83], v92 offset0:56 offset1:60
	v_pk_mul_f32 v[92:93], v[162:163], v[120:121] op_sel_hi:[0,1]
	v_pk_mul_f32 v[94:95], v[162:163], v[122:123] op_sel_hi:[0,1]
	s_waitcnt lgkmcnt(1)
	v_mfma_f32_16x16x32_bf16 v[76:79], v[84:87], v[24:27], v[76:79]
	v_cvt_pk_bf16_f32 v88, v88, v89
	v_cvt_pk_bf16_f32 v89, v90, v91
	v_cvt_pk_bf16_f32 v92, v92, v93
	v_mfma_f32_16x16x32_bf16 v[72:75], v[84:87], v[32:35], v[72:75]
	ds_read2_b64 v[84:87], v100 offset1:4
	v_cvt_pk_bf16_f32 v93, v94, v95
	v_mov_b32_e32 v226, v88
	v_mov_b32_e32 v227, v89
	s_nop 1
	v_permlane16_swap_b32 v224, v226
	v_permlane16_swap_b32 v225, v227
	global_store_dwordx4 v[232:233], v[224:227], off offset:192
	s_waitcnt lgkmcnt(1)
	v_mfma_f32_16x16x32_bf16 v[76:79], v[80:83], v[28:31], v[76:79]
	v_mov_b32_e32 v222, v92
	v_mov_b32_e32 v223, v93
	s_nop 1
	v_permlane16_swap_b32 v220, v222
	v_permlane16_swap_b32 v221, v223
	global_store_dwordx4 v[234:235], v[220:223], off offset:192
	ds_read2_b64 v[92:95], v100 offset0:16 offset1:20
	v_pk_mul_f32 v[68:69], v[160:161], v[68:69] op_sel_hi:[0,1]
	v_mfma_f32_16x16x32_bf16 v[72:75], v[80:83], v[40:43], v[72:75]
	ds_read2_b64 v[80:83], v100 offset0:8 offset1:12
	v_cvt_pk_bf16_f32 v68, v68, v69
	v_pk_mul_f32 v[96:97], v[160:161], v[132:133] op_sel_hi:[0,1]
	s_waitcnt lgkmcnt(2)
	v_mfma_f32_16x16x32_bf16 v[88:91], v[84:87], v[16:19], 0
	v_mul_f32_e64 v98, v160, v134
	v_mul_f32_e64 v99, v160, v135
	v_cvt_pk_bf16_f32 v96, v96, v97
	v_cvt_pk_bf16_f32 v97, v98, v99
	v_mfma_f32_16x16x32_bf16 v[84:87], v[84:87], v[60:63], 0
	v_mov_b32_e32 v228, v96
	v_mov_b32_e32 v229, v97
	v_pk_mul_f32 v[96:97], v[162:163], v[128:129] op_sel_hi:[0,1]
	v_pk_mul_f32 v[98:99], v[162:163], v[130:131] op_sel_hi:[0,1]
	s_waitcnt lgkmcnt(0)
	v_mfma_f32_16x16x32_bf16 v[88:91], v[80:83], v[12:15], v[88:91]
	v_cvt_pk_bf16_f32 v96, v96, v97
	v_cvt_pk_bf16_f32 v97, v98, v99
	v_mov_b32_e32 v216, v96
	v_mov_b32_e32 v217, v97
	v_mfma_f32_16x16x32_bf16 v[80:83], v[80:83], v[56:59], v[84:87]
	v_mul_f32_e64 v96, v160, v140
	v_mul_f32_e64 v97, v160, v141
	v_pk_mul_f32 v[98:99], v[160:161], v[142:143] op_sel_hi:[0,1]
	v_cvt_pk_bf16_f32 v96, v96, v97
	ds_read2_b64 v[84:87], v100 offset0:24 offset1:28
	v_mfma_f32_16x16x32_bf16 v[88:91], v[92:95], v[8:11], v[88:91]
	v_cvt_pk_bf16_f32 v97, v98, v99
	v_mov_b32_e32 v230, v96
	v_mov_b32_e32 v231, v97
	s_nop 1
	v_permlane16_swap_b32 v228, v230
	v_permlane16_swap_b32 v229, v231
	global_store_dwordx4 v[232:233], v[228:231], off offset:256
	v_pk_mul_f32 v[96:97], v[162:163], v[136:137] op_sel_hi:[0,1]
	v_mfma_f32_16x16x32_bf16 v[80:83], v[92:95], v[52:55], v[80:83]
	ds_read2_b64 v[92:95], v100 offset0:32 offset1:36
	v_pk_mul_f32 v[98:99], v[162:163], v[138:139] op_sel_hi:[0,1]
	v_cvt_pk_bf16_f32 v96, v96, v97
	s_waitcnt lgkmcnt(1)
	v_mfma_f32_16x16x32_bf16 v[88:91], v[84:87], v[4:7], v[88:91]
	v_cvt_pk_bf16_f32 v97, v98, v99
	v_mov_b32_e32 v218, v96
	v_mov_b32_e32 v219, v97
	s_nop 1
	v_permlane16_swap_b32 v216, v218
	v_permlane16_swap_b32 v217, v219
	global_store_dwordx4 v[234:235], v[216:219], off offset:256
	v_pk_mul_f32 v[96:97], v[160:161], v[148:149] op_sel_hi:[0,1]
	v_mfma_f32_16x16x32_bf16 v[80:83], v[84:87], v[48:51], v[80:83]
	ds_read2_b64 v[84:87], v100 offset0:40 offset1:44
	v_pk_mul_f32 v[98:99], v[160:161], v[150:151] op_sel_hi:[0,1]
	v_cvt_pk_bf16_f32 v96, v96, v97
	s_waitcnt lgkmcnt(1)
	v_mfma_f32_16x16x32_bf16 v[88:91], v[92:95], v[0:3], v[88:91]
	v_cvt_pk_bf16_f32 v97, v98, v99
	v_mov_b32_e32 v224, v96
	v_mov_b32_e32 v225, v97
	v_pk_mul_f32 v[96:97], v[162:163], v[144:145] op_sel_hi:[0,1]
	v_mfma_f32_16x16x32_bf16 v[80:83], v[92:95], v[44:47], v[80:83]
	ds_read2_b64 v[92:95], v100 offset0:48 offset1:52
	v_pk_mul_f32 v[98:99], v[162:163], v[146:147] op_sel_hi:[0,1]
	v_cvt_pk_bf16_f32 v96, v96, v97
	s_waitcnt lgkmcnt(1)
	v_mfma_f32_16x16x32_bf16 v[88:91], v[84:87], v[20:23], v[88:91]
	v_cvt_pk_bf16_f32 v97, v98, v99
	v_mov_b32_e32 v220, v96
	v_mov_b32_e32 v221, v97
	v_pk_mul_f32 v[96:97], v[160:161], v[156:157] op_sel_hi:[0,1]
	v_mfma_f32_16x16x32_bf16 v[80:83], v[84:87], v[36:39], v[80:83]
	ds_read2_b64 v[84:87], v100 offset0:56 offset1:60
	v_add_u32_e32 v100, v200, v210
	v_pk_mul_f32 v[98:99], v[160:161], v[158:159] op_sel_hi:[0,1]
	s_waitcnt lgkmcnt(1)
	v_mfma_f32_16x16x32_bf16 v[88:91], v[92:95], v[24:27], v[88:91]
	v_cvt_pk_bf16_f32 v96, v96, v97
	v_cvt_pk_bf16_f32 v97, v98, v99
	v_mov_b32_e32 v226, v96
	v_mov_b32_e32 v227, v97
	s_nop 1
	v_permlane16_swap_b32 v224, v226
	v_permlane16_swap_b32 v225, v227
	global_store_dwordx4 v[232:233], v[224:227], off offset:320
	v_mfma_f32_16x16x32_bf16 v[80:83], v[92:95], v[32:35], v[80:83]
	ds_read2_b64 v[92:95], v100 offset1:4
	v_pk_mul_f32 v[96:97], v[162:163], v[152:153] op_sel_hi:[0,1]
	v_pk_mul_f32 v[98:99], v[162:163], v[154:155] op_sel_hi:[0,1]
	s_waitcnt lgkmcnt(1)
	v_mfma_f32_16x16x32_bf16 v[88:91], v[84:87], v[28:31], v[88:91]
	v_cvt_pk_bf16_f32 v96, v96, v97
	v_cvt_pk_bf16_f32 v97, v98, v99
	v_mov_b32_e32 v228, v178
	v_mov_b32_e32 v229, v179
	v_mfma_f32_16x16x32_bf16 v[80:83], v[84:87], v[40:43], v[80:83]
	ds_read2_b64 v[84:87], v100 offset0:8 offset1:12
	v_mov_b32_e32 v230, v168
	v_mov_b32_e32 v231, v169
	s_nop 1
	v_permlane16_swap_b32 v228, v230
	v_permlane16_swap_b32 v229, v231
	global_store_dwordx4 v[234:235], v[228:231], off
	v_mov_b32_e32 v222, v96
	v_mov_b32_e32 v223, v97
	s_nop 1
	v_permlane16_swap_b32 v220, v222
	v_permlane16_swap_b32 v221, v223
	global_store_dwordx4 v[234:235], v[220:223], off offset:320
	s_waitcnt lgkmcnt(1)
	v_mfma_f32_16x16x32_bf16 v[16:19], v[92:95], v[16:19], 0
	v_mfma_f32_16x16x32_bf16 v[60:63], v[92:95], v[60:63], 0
	ds_read2_b64 v[92:95], v100 offset0:16 offset1:20
	s_waitcnt lgkmcnt(1)
	v_mfma_f32_16x16x32_bf16 v[12:15], v[84:87], v[12:15], v[16:19]
	s_nop 3
	v_mul_f32_e64 v16, v160, v70
	v_mul_f32_e64 v17, v160, v71
	v_cvt_pk_bf16_f32 v69, v16, v17
	v_mfma_f32_16x16x32_bf16 v[16:19], v[84:87], v[56:59], v[60:63]
	ds_read2_b64 v[56:59], v100 offset0:24 offset1:28
	v_mov_b32_e32 v216, v68
	v_mov_b32_e32 v217, v69
	s_nop 0
	v_pk_mul_f32 v[60:61], v[162:163], v[64:65] op_sel_hi:[0,1]
	s_waitcnt lgkmcnt(1)
	v_mfma_f32_16x16x32_bf16 v[8:11], v[92:95], v[8:11], v[12:15]
	v_cvt_pk_bf16_f32 v60, v60, v61
	s_nop 1
	v_pk_mul_f32 v[12:13], v[162:163], v[66:67] op_sel_hi:[0,1]
	v_cvt_pk_bf16_f32 v61, v12, v13
	v_mfma_f32_16x16x32_bf16 v[12:15], v[92:95], v[52:55], v[16:19]
	v_mul_f32_e64 v52, v160, v76
	v_mul_f32_e64 v53, v160, v77
	v_cvt_pk_bf16_f32 v52, v52, v53
	v_mov_b32_e32 v224, v60
	v_mov_b32_e32 v225, v61
	ds_read2_b64 v[16:19], v100 offset0:32 offset1:36
	s_waitcnt lgkmcnt(1)
	v_mfma_f32_16x16x32_bf16 v[4:7], v[56:59], v[4:7], v[8:11]
	s_nop 2
	v_mul_f32_e64 v8, v160, v78
	v_mul_f32_e64 v9, v160, v79
	v_cvt_pk_bf16_f32 v53, v8, v9
	v_mfma_f32_16x16x32_bf16 v[8:11], v[56:59], v[48:51], v[12:15]
	v_mul_f32_e64 v48, v162, v72
	v_mul_f32_e64 v49, v162, v73
	v_cvt_pk_bf16_f32 v48, v48, v49
	v_mov_b32_e32 v218, v52
	v_mov_b32_e32 v219, v53
	s_nop 1
	v_permlane16_swap_b32 v216, v218
	v_permlane16_swap_b32 v217, v219
	global_store_dwordx4 v[232:233], v[216:219], off offset:384
	ds_read2_b64 v[12:15], v100 offset0:40 offset1:44
	s_waitcnt lgkmcnt(1)
	v_mfma_f32_16x16x32_bf16 v[0:3], v[16:19], v[0:3], v[4:7]
	s_nop 2
	v_mul_f32_e64 v4, v162, v74
	v_mul_f32_e64 v5, v162, v75
	v_cvt_pk_bf16_f32 v49, v4, v5
	v_mfma_f32_16x16x32_bf16 v[4:7], v[16:19], v[44:47], v[8:11]
	v_mul_f32_e64 v16, v160, v88
	v_mul_f32_e64 v17, v160, v89
	v_mov_b32_e32 v226, v48
	v_mov_b32_e32 v227, v49
	s_nop 1
	v_permlane16_swap_b32 v224, v226
	v_permlane16_swap_b32 v225, v227
	global_store_dwordx4 v[234:235], v[224:227], off offset:384
	ds_read2_b64 v[8:11], v100 offset0:48 offset1:52
	s_waitcnt lgkmcnt(1)
	v_mfma_f32_16x16x32_bf16 v[0:3], v[12:15], v[20:23], v[0:3]
	v_cvt_pk_bf16_f32 v22, v16, v17
	ds_read2_b64 v[16:19], v100 offset0:56 offset1:60
	v_pk_mul_f32 v[20:21], v[160:161], v[90:91] op_sel_hi:[0,1]
	s_waitcnt lgkmcnt(1)
	v_mfma_f32_16x16x32_bf16 v[0:3], v[8:11], v[24:27], v[0:3]
	v_cvt_pk_bf16_f32 v23, v20, v21
	v_mov_b32_e32 v228, v22
	v_mov_b32_e32 v229, v23
	v_mfma_f32_16x16x32_bf16 v[4:7], v[12:15], v[36:39], v[4:7]
	v_mul_f32_e64 v12, v162, v80
	v_mul_f32_e64 v13, v162, v81
	v_pk_mul_f32 v[14:15], v[162:163], v[82:83] op_sel_hi:[0,1]
	v_cvt_pk_bf16_f32 v12, v12, v13
	s_waitcnt lgkmcnt(0)
	v_mfma_f32_16x16x32_bf16 v[0:3], v[16:19], v[28:31], v[0:3]
	v_cvt_pk_bf16_f32 v13, v14, v15
	v_mov_b32_e32 v220, v12
	v_mov_b32_e32 v221, v13
	s_nop 5
	v_pk_mul_f32 v[12:13], v[160:161], v[0:1] op_sel_hi:[0,1]
	v_pk_mul_f32 v[14:15], v[160:161], v[2:3] op_sel_hi:[0,1]
	v_mfma_f32_16x16x32_bf16 v[0:3], v[8:11], v[32:35], v[4:7]
	v_mfma_f32_16x16x32_bf16 v[0:3], v[16:19], v[40:43], v[0:3]
	s_nop 1
	v_cvt_pk_bf16_f32 v4, v12, v13
	v_cvt_pk_bf16_f32 v5, v14, v15
	v_mov_b32_e32 v230, v4
	v_mov_b32_e32 v231, v5
	s_nop 1
	v_permlane16_swap_b32 v228, v230
	v_permlane16_swap_b32 v229, v231
	global_store_dwordx4 v[232:233], v[228:231], off offset:448
	s_nop 2
	v_pk_mul_f32 v[0:1], v[162:163], v[0:1] op_sel_hi:[0,1]
	v_pk_mul_f32 v[2:3], v[162:163], v[2:3] op_sel_hi:[0,1]
	v_cvt_pk_bf16_f32 v0, v0, v1
	v_cvt_pk_bf16_f32 v1, v2, v3
	v_mov_b32_e32 v222, v0
	v_mov_b32_e32 v223, v1
	s_nop 1
	v_permlane16_swap_b32 v220, v222
	v_permlane16_swap_b32 v221, v223
	global_store_dwordx4 v[234:235], v[220:223], off offset:448
	s_barrier
	s_cbranch_scc0 .LBB0_501
